# GEMM epilogues: redundant vmcnt(0) (which also waited for store acks) removed from the q/k row groups of the input-projection epilogue; final epilogue waits count only the prep loads
# baseline (speedup 1.0000x reference)
;     __device__ __forceinline__ void run(const f32x4 (&acc)[2][2][4][2], const Unit& u, int wr, int wc, int fr, int fq, const int nai, LAS unsigned char* lds, const int ui) const {
;     ...
;             for (int m = 0; m < 4; ++m) {
;                 const int r = u.pm * 256 + ai * 128 + wr * 64 + m * 16 + fr;
;                 const float rs = RT[ai * 128 + wr * 64 + m * 16 + fr];
;                 f32x4 v[2][2];
; #pragma unroll
;                 for (int bj = 0; bj < 2; ++bj)
; #pragma unroll
;                     for (int n = 0; n < 2; ++n) v[bj][n] = acc[ai][bj][m][n] * rs;
;                 if (isqk) {
;                     float q2 = 0.f;
; #pragma unroll
;                     for (int bj = 0; bj < 2; ++bj)
; #pragma unroll
;                         for (int n = 0; n < 2; ++n) { const f32x4 x = v[bj][n]; q2 += (x[0] * x[0] + x[1] * x[1]) + (x[2] * x[2] + x[3] * x[3]); }
;                     q2 += __shfl_xor(q2, 16); q2 += __shfl_xor(q2, 32);
;                     const float rn = rsqrtf(q2 * (1.0f / 64.0f) + EPS);
; #pragma unroll
;                     for (int bj = 0; bj < 2; ++bj)
; #pragma unroll
;                         for (int n = 0; n < 2; ++n) v[bj][n] = v[bj][n] * rn * gv[bj][n];
;                     int b, t; row_bt(r, b, t);
; #pragma unroll
;                     for (int n = 0; n < 2; ++n) {
;                         f32x4 o; o[0] = __shfl_xor(v[0][n][0], 16); o[1] = __shfl_xor(v[0][n][1], 16); o[2] = __shfl_xor(v[0][n][2], 16); o[3] = __shfl_xor(v[0][n][3], 16);
;                         f32x4 c, s;
; #pragma unroll
;                         for (int i = 0; i < 4; ++i) {
;                             const float angf = (float)t * ROPE_INV[4 * n + i];
;                             const float pr_ = angf * 0.15915494f, er_ = __builtin_fmaf(angf, 0.15915494f, -pr_);
;                             const float rev = __builtin_amdgcn_fractf(pr_) + __builtin_fmaf(angf, (float)(0.15915494309189535 - (double)0.15915494f), er_);
;                             c[i] = __builtin_amdgcn_cosf(rev); s[i] = __builtin_amdgcn_sinf(rev); }
;                         v[0][n] = (fq == 0) ? (v[0][n] * c - o * s) : ((fq == 1) ? (v[0][n] * c + o * s) : v[0][n]);
;                     }
; #pragma unroll
;                     for (int bj = 0; bj < 2; ++bj)
; #pragma unroll
;                         for (int n = 0; n < 2; ++n) v[bj][n] = v[bj][n] * qs;
;                 }
.LBB0_213:
	s_lshl_b32 s8, s3, 8
	v_mov_b64_e32 v[138:139], s[16:17]
	s_ashr_i32 s9, s8, 31
	v_mad_i64_i32 v[138:139], s[10:11], v0, s33, v[138:139]
	v_cvt_pk_bf16_f32 v140, v146, v147
	ds_read_b32 v146, v226 offset:64
	v_lshl_add_u64 v[138:139], s[8:9], 1, v[138:139]
	s_lshl_b32 s6, s66, 1
	v_lshl_add_u64 v[138:139], v[138:139], 0, s[6:7]
	v_lshlrev_b32_e32 v0, 1, v162
	v_lshl_add_u64 v[142:143], v[138:139], 0, v[0:1]
	v_cvt_pk_bf16_f32 v138, v176, v177
	v_cvt_pk_bf16_f32 v139, v178, v179
	v_cvt_pk_bf16_f32 v141, v182, v183
	global_store_dwordx4 v[142:143], v[138:141], off
	s_waitcnt lgkmcnt(0)
	v_pk_mul_f32 v[144:145], v[136:137], v[146:147] op_sel_hi:[1,0]
	v_pk_mul_f32 v[130:131], v[130:131], v[146:147] op_sel_hi:[1,0]
	v_cvt_pk_bf16_f32 v138, v172, v173
	v_cvt_pk_bf16_f32 v139, v148, v149
	v_cvt_pk_bf16_f32 v140, v152, v153
	v_cvt_pk_bf16_f32 v141, v150, v151
	global_store_dwordx4 v[142:143], v[138:141], off offset:64
	v_pk_mul_f32 v[142:143], v[134:135], v[146:147] op_sel_hi:[1,0]
	v_pk_mul_f32 v[148:149], v[132:133], v[146:147] op_sel_hi:[1,0]
	v_pk_mul_f32 v[132:133], v[128:129], v[146:147] op_sel_hi:[1,0]
	v_pk_mul_f32 v[138:139], v[126:127], v[146:147] op_sel_hi:[1,0]
	v_pk_mul_f32 v[134:135], v[124:125], v[146:147] op_sel_hi:[1,0]
	v_pk_mul_f32 v[136:137], v[122:123], v[146:147] op_sel_hi:[1,0]
	s_and_b64 vcc, exec, s[40:41]
	v_add_u32_e32 v176, s2, v209
	s_cbranch_vccnz .LBB0_227
	v_pk_mul_f32 v[122:123], v[144:145], v[144:145]
	v_pk_mul_f32 v[124:125], v[142:143], v[142:143]
	s_mov_b32 s3, 0x800000
	v_pk_mov_b32 v[126:127], v[124:125], v[122:123] op_sel:[1,0]
	v_mov_b32_e32 v125, v123
	v_pk_add_f32 v[122:123], v[126:127], v[124:125]
	v_pk_mul_f32 v[124:125], v[148:149], v[148:149]
	v_pk_add_f32 v[122:123], v[122:123], v[122:123] op_sel_hi:[0,1]
	v_pk_mul_f32 v[126:127], v[130:131], v[130:131]
	v_mul_f32_e32 v122, v138, v138
	v_pk_mov_b32 v[128:129], v[126:127], v[124:125] op_sel:[1,0]
	v_mov_b32_e32 v127, v125
	v_pk_add_f32 v[124:125], v[128:129], v[126:127]
	v_pk_fma_f32 v[126:127], v[138:139], v[138:139], v[122:123] op_sel_hi:[1,1,0]
	v_mul_f32_e32 v122, v132, v132
	v_pk_add_f32 v[124:125], v[124:125], v[124:125] op_sel_hi:[0,1]
	v_pk_fma_f32 v[128:129], v[132:133], v[132:133], v[122:123] op_sel_hi:[1,1,0]
	v_mul_f32_e32 v126, v136, v136
	v_mul_f32_e32 v128, v137, v137
	v_mul_f32_e32 v122, v134, v134
	v_mul_f32_e32 v124, v135, v135
	v_pk_add_f32 v[126:127], v[126:127], v[128:129]
	v_pk_add_f32 v[122:123], v[122:123], v[124:125]
	s_nop 0
	v_pk_add_f32 v[122:123], v[126:127], v[122:123]
	s_nop 0
	v_add_f32_e32 v122, v122, v123
	ds_bpermute_b32 v123, v207, v122
	s_waitcnt lgkmcnt(0)
	v_add_f32_e32 v122, v122, v123
	ds_bpermute_b32 v123, v208, v122
	s_waitcnt lgkmcnt(0)
	v_add_f32_e32 v122, v122, v123
	v_fmamk_f32 v122, v122, 0x3c800000, v214
	v_mul_f32_e32 v123, 0x4b800000, v122
	v_cmp_gt_f32_e32 vcc, s3, v122
	s_nop 1
	v_cndmask_b32_e32 v122, v122, v123, vcc
	v_rsq_f32_e32 v122, v122
	s_nop 0
	v_mul_f32_e32 v123, 0x45800000, v122
	v_cndmask_b32_e32 v140, v122, v123, vcc
	v_mov_b32_e32 v141, v140
	v_pk_mul_f32 v[124:125], v[144:145], v[140:141] op_sel_hi:[1,0]
	v_pk_mul_f32 v[122:123], v[142:143], v[140:141] op_sel_hi:[1,0]
	s_nop 0
	v_pk_mul_f32 v[144:145], v[56:57], v[124:125]
	v_mul_hi_i32 v124, v176, s27
	v_lshrrev_b32_e32 v125, 31, v124
	v_ashrrev_i32_e32 v124, 12, v124
	v_add_u32_e32 v124, v124, v125
	v_mul_i32_i24_e32 v124, 0x2010, v124
	v_sub_u32_e32 v124, v176, v124
	v_cvt_f32_i32_e32 v175, v124
	v_pk_mul_f32 v[142:143], v[54:55], v[122:123]
	ds_bpermute_b32 v122, v207, v142
	ds_bpermute_b32 v123, v207, v143
	v_mul_f32_e32 v124, 0.15915494, v175
	v_fma_f32 v125, v175, 0.15915494, -v124
	v_fract_f32_e32 v124, v124
	v_fmac_f32_e32 v125, 0x31dc9c88, v175
	v_add_f32_e32 v124, v124, v125
	v_mul_f32_e32 v125, 0x3e4693af, v175
	v_mul_f32_e32 v127, 0.15915494, v125
	v_fma_f32 v128, v125, 0.15915494, -v127
	v_fract_f32_e32 v127, v127
	v_fmac_f32_e32 v128, 0x31dc9c88, v125
	v_add_f32_e32 v125, v127, v128
	v_mul_f32_e32 v128, 0x3d1a08c8, v175
	v_mul_f32_e32 v129, 0.15915494, v128
	v_fma_f32 v152, v128, 0.15915494, -v129
	v_fract_f32_e32 v129, v129
	v_fmac_f32_e32 v152, 0x31dc9c88, v128
	v_add_f32_e32 v128, v129, v152
	v_cos_f32_e32 v152, v128
	v_sin_f32_e32 v172, v128
	v_mul_f32_e32 v128, 0x3beef74e, v175
	v_mul_f32_e32 v129, 0.15915494, v128
	v_fma_f32 v153, v128, 0.15915494, -v129
	v_fract_f32_e32 v129, v129
	v_fmac_f32_e32 v153, 0x31dc9c88, v128
	ds_bpermute_b32 v150, v207, v144
	ds_bpermute_b32 v151, v207, v145
	v_add_f32_e32 v128, v129, v153
	v_cos_f32_e32 v126, v124
	v_sin_f32_e32 v124, v124
	v_cos_f32_e32 v127, v125
	v_sin_f32_e32 v125, v125
	v_cos_f32_e32 v153, v128
	v_sin_f32_e32 v173, v128
	v_mov_b32_e32 v146, v140
	v_mov_b32_e32 v147, v140
	v_cmp_lt_i32_e32 vcc, 0, v202
	s_and_saveexec_b64 s[10:11], vcc
	s_xor_b64 s[10:11], exec, s[10:11]
	s_cbranch_execz .LBB0_218
	v_cmp_eq_u32_e32 vcc, 1, v202
	s_and_saveexec_b64 s[14:15], vcc
	s_cbranch_execz .LBB0_217
	v_pk_mul_f32 v[128:129], v[152:153], v[144:145]
	v_pk_mul_f32 v[126:127], v[126:127], v[142:143]
	s_waitcnt lgkmcnt(0)
	v_pk_fma_f32 v[144:145], v[172:173], v[150:151], v[128:129]
	v_pk_fma_f32 v[142:143], v[124:125], v[122:123], v[126:127]

;     __device__ __forceinline__ void run(const f32x4 (&acc)[2][2][4][2], const Unit& u, int wr, int wc, int fr, int fq, const int nai, LAS unsigned char* lds, const int ui) const {
;     ...
;             for (int m = 0; m < 4; ++m) {
;                 const int r = u.pm * 256 + ai * 128 + wr * 64 + m * 16 + fr;
;                 const float rs = RT[ai * 128 + wr * 64 + m * 16 + fr];
;                 f32x4 v[2][2];
; #pragma unroll
;                 for (int bj = 0; bj < 2; ++bj)
; #pragma unroll
;                     for (int n = 0; n < 2; ++n) v[bj][n] = acc[ai][bj][m][n] * rs;
;                 if (isqk) {
;                     float q2 = 0.f;
; #pragma unroll
;                     for (int bj = 0; bj < 2; ++bj)
; #pragma unroll
;                         for (int n = 0; n < 2; ++n) { const f32x4 x = v[bj][n]; q2 += (x[0] * x[0] + x[1] * x[1]) + (x[2] * x[2] + x[3] * x[3]); }
;                     q2 += __shfl_xor(q2, 16); q2 += __shfl_xor(q2, 32);
;                     const float rn = rsqrtf(q2 * (1.0f / 64.0f) + EPS);
; #pragma unroll
;                     for (int bj = 0; bj < 2; ++bj)
; #pragma unroll
;                         for (int n = 0; n < 2; ++n) v[bj][n] = v[bj][n] * rn * gv[bj][n];
;                     int b, t; row_bt(r, b, t);
; #pragma unroll
;                     for (int n = 0; n < 2; ++n) {
;                         f32x4 o; o[0] = __shfl_xor(v[0][n][0], 16); o[1] = __shfl_xor(v[0][n][1], 16); o[2] = __shfl_xor(v[0][n][2], 16); o[3] = __shfl_xor(v[0][n][3], 16);
;                         f32x4 c, s;
; #pragma unroll
;                         for (int i = 0; i < 4; ++i) {
;                             const float angf = (float)t * ROPE_INV[4 * n + i];
;                             const float pr_ = angf * 0.15915494f, er_ = __builtin_fmaf(angf, 0.15915494f, -pr_);
;                             const float rev = __builtin_amdgcn_fractf(pr_) + __builtin_fmaf(angf, (float)(0.15915494309189535 - (double)0.15915494f), er_);
;                             c[i] = __builtin_amdgcn_cosf(rev); s[i] = __builtin_amdgcn_sinf(rev); }
;                         v[0][n] = (fq == 0) ? (v[0][n] * c - o * s) : ((fq == 1) ? (v[0][n] * c + o * s) : v[0][n]);
;                     }
; #pragma unroll
;                     for (int bj = 0; bj < 2; ++bj)
; #pragma unroll
;                         for (int n = 0; n < 2; ++n) v[bj][n] = v[bj][n] * qs;
;                 }
.LBB0_227:
	v_mov_b64_e32 v[122:123], s[16:17]
	v_mad_i64_i32 v[122:123], s[10:11], v176, s33, v[122:123]
	v_cvt_pk_bf16_f32 v124, v130, v131
	ds_read_b32 v130, v226 offset:128
	v_lshl_add_u64 v[122:123], s[8:9], 1, v[122:123]
	v_lshl_add_u64 v[122:123], v[122:123], 0, s[6:7]
	v_lshl_add_u64 v[126:127], v[122:123], 0, v[0:1]
	v_cvt_pk_bf16_f32 v122, v142, v143
	v_cvt_pk_bf16_f32 v123, v144, v145
	v_cvt_pk_bf16_f32 v125, v148, v149
	global_store_dwordx4 v[126:127], v[122:125], off
	s_waitcnt lgkmcnt(0)
	v_pk_mul_f32 v[128:129], v[120:121], v[130:131] op_sel_hi:[1,0]
	v_pk_mul_f32 v[114:115], v[114:115], v[130:131] op_sel_hi:[1,0]
	v_cvt_pk_bf16_f32 v122, v138, v139
	v_cvt_pk_bf16_f32 v123, v132, v133
	v_cvt_pk_bf16_f32 v124, v136, v137
	v_cvt_pk_bf16_f32 v125, v134, v135
	global_store_dwordx4 v[126:127], v[122:125], off offset:64
	v_pk_mul_f32 v[126:127], v[118:119], v[130:131] op_sel_hi:[1,0]
	v_pk_mul_f32 v[132:133], v[116:117], v[130:131] op_sel_hi:[1,0]
	v_pk_mul_f32 v[116:117], v[112:113], v[130:131] op_sel_hi:[1,0]
	v_pk_mul_f32 v[122:123], v[110:111], v[130:131] op_sel_hi:[1,0]
	v_pk_mul_f32 v[118:119], v[108:109], v[130:131] op_sel_hi:[1,0]
	v_pk_mul_f32 v[120:121], v[106:107], v[130:131] op_sel_hi:[1,0]
	s_and_b64 vcc, exec, s[40:41]
	v_add_u32_e32 v142, s2, v210
	s_cbranch_vccnz .LBB0_241
	v_pk_mul_f32 v[106:107], v[128:129], v[128:129]
	v_pk_mul_f32 v[108:109], v[126:127], v[126:127]
	s_mov_b32 s3, 0x800000
	v_pk_mov_b32 v[110:111], v[108:109], v[106:107] op_sel:[1,0]
	v_mov_b32_e32 v109, v107
	v_pk_add_f32 v[106:107], v[110:111], v[108:109]
	v_pk_mul_f32 v[108:109], v[132:133], v[132:133]
	v_pk_add_f32 v[106:107], v[106:107], v[106:107] op_sel_hi:[0,1]
	v_pk_mul_f32 v[110:111], v[114:115], v[114:115]
	v_mul_f32_e32 v106, v122, v122
	v_pk_mov_b32 v[112:113], v[110:111], v[108:109] op_sel:[1,0]
	v_mov_b32_e32 v111, v109
	v_pk_add_f32 v[108:109], v[112:113], v[110:111]
	v_pk_fma_f32 v[110:111], v[122:123], v[122:123], v[106:107] op_sel_hi:[1,1,0]
	v_mul_f32_e32 v106, v116, v116
	v_pk_add_f32 v[108:109], v[108:109], v[108:109] op_sel_hi:[0,1]
	v_pk_fma_f32 v[112:113], v[116:117], v[116:117], v[106:107] op_sel_hi:[1,1,0]
	v_mul_f32_e32 v110, v120, v120
	v_mul_f32_e32 v112, v121, v121
	v_mul_f32_e32 v106, v118, v118
	v_mul_f32_e32 v108, v119, v119
	v_pk_add_f32 v[110:111], v[110:111], v[112:113]
	v_pk_add_f32 v[106:107], v[106:107], v[108:109]
	s_nop 0
	v_pk_add_f32 v[106:107], v[110:111], v[106:107]
	s_nop 0
	v_add_f32_e32 v106, v106, v107
	ds_bpermute_b32 v107, v207, v106
	s_waitcnt lgkmcnt(0)
	v_add_f32_e32 v106, v106, v107
	ds_bpermute_b32 v107, v208, v106
	s_waitcnt lgkmcnt(0)
	v_add_f32_e32 v106, v106, v107
	v_fmamk_f32 v106, v106, 0x3c800000, v214
	v_mul_f32_e32 v107, 0x4b800000, v106
	v_cmp_gt_f32_e32 vcc, s3, v106
	s_nop 1
	v_cndmask_b32_e32 v106, v106, v107, vcc
	v_rsq_f32_e32 v106, v106
	s_nop 0
	v_mul_f32_e32 v107, 0x45800000, v106
	v_cndmask_b32_e32 v124, v106, v107, vcc
	v_mov_b32_e32 v125, v124
	v_pk_mul_f32 v[108:109], v[128:129], v[124:125] op_sel_hi:[1,0]
	v_pk_mul_f32 v[106:107], v[126:127], v[124:125] op_sel_hi:[1,0]
	s_nop 0
	v_pk_mul_f32 v[128:129], v[56:57], v[108:109]
	v_mul_hi_i32 v108, v142, s27
	v_lshrrev_b32_e32 v109, 31, v108
	v_ashrrev_i32_e32 v108, 12, v108
	v_add_u32_e32 v108, v108, v109
	v_mul_i32_i24_e32 v108, 0x2010, v108
	v_sub_u32_e32 v108, v142, v108
	v_cvt_f32_i32_e32 v141, v108
	v_pk_mul_f32 v[126:127], v[54:55], v[106:107]
	ds_bpermute_b32 v106, v207, v126
	ds_bpermute_b32 v107, v207, v127
	v_mul_f32_e32 v108, 0.15915494, v141
	v_fma_f32 v109, v141, 0.15915494, -v108
	v_fract_f32_e32 v108, v108
	v_fmac_f32_e32 v109, 0x31dc9c88, v141
	v_add_f32_e32 v108, v108, v109
	v_mul_f32_e32 v109, 0x3e4693af, v141
	v_mul_f32_e32 v111, 0.15915494, v109
	v_fma_f32 v112, v109, 0.15915494, -v111
	v_fract_f32_e32 v111, v111
	v_fmac_f32_e32 v112, 0x31dc9c88, v109
	v_add_f32_e32 v109, v111, v112
	v_mul_f32_e32 v112, 0x3d1a08c8, v141
	v_mul_f32_e32 v113, 0.15915494, v112
	v_fma_f32 v136, v112, 0.15915494, -v113
	v_fract_f32_e32 v113, v113
	v_fmac_f32_e32 v136, 0x31dc9c88, v112
	v_add_f32_e32 v112, v113, v136
	v_cos_f32_e32 v136, v112
	v_sin_f32_e32 v138, v112
	v_mul_f32_e32 v112, 0x3beef74e, v141
	v_mul_f32_e32 v113, 0.15915494, v112
	v_fma_f32 v137, v112, 0.15915494, -v113
	v_fract_f32_e32 v113, v113
	v_fmac_f32_e32 v137, 0x31dc9c88, v112
	ds_bpermute_b32 v134, v207, v128
	ds_bpermute_b32 v135, v207, v129
	v_add_f32_e32 v112, v113, v137
	v_cos_f32_e32 v110, v108
	v_sin_f32_e32 v108, v108
	v_cos_f32_e32 v111, v109
	v_sin_f32_e32 v109, v109
	v_cos_f32_e32 v137, v112
	v_sin_f32_e32 v139, v112
	v_mov_b32_e32 v130, v124
	v_mov_b32_e32 v131, v124
	v_cmp_lt_i32_e32 vcc, 0, v202
	s_and_saveexec_b64 s[10:11], vcc
	s_xor_b64 s[10:11], exec, s[10:11]
	s_cbranch_execz .LBB0_232
	v_cmp_eq_u32_e32 vcc, 1, v202
	s_and_saveexec_b64 s[14:15], vcc
	s_cbranch_execz .LBB0_231
	v_pk_mul_f32 v[112:113], v[136:137], v[128:129]
	v_pk_mul_f32 v[110:111], v[110:111], v[126:127]
	s_waitcnt lgkmcnt(0)
	v_pk_fma_f32 v[128:129], v[138:139], v[134:135], v[112:113]
	v_pk_fma_f32 v[126:127], v[108:109], v[106:107], v[110:111]

;     __device__ __forceinline__ void run(const f32x4 (&acc)[2][2][4][2], const Unit& u, int wr, int wc, int fr, int fq, const int nai, LAS unsigned char* lds, const int ui) const {
;     ...
;             for (int m = 0; m < 4; ++m) {
;                 const int r = u.pm * 256 + ai * 128 + wr * 64 + m * 16 + fr;
;                 const float rs = RT[ai * 128 + wr * 64 + m * 16 + fr];
;                 f32x4 v[2][2];
; #pragma unroll
;                 for (int bj = 0; bj < 2; ++bj)
; #pragma unroll
;                     for (int n = 0; n < 2; ++n) v[bj][n] = acc[ai][bj][m][n] * rs;
;                 if (isqk) {
;                     float q2 = 0.f;
; #pragma unroll
;                     for (int bj = 0; bj < 2; ++bj)
; #pragma unroll
;                         for (int n = 0; n < 2; ++n) { const f32x4 x = v[bj][n]; q2 += (x[0] * x[0] + x[1] * x[1]) + (x[2] * x[2] + x[3] * x[3]); }
;                     q2 += __shfl_xor(q2, 16); q2 += __shfl_xor(q2, 32);
;                     const float rn = rsqrtf(q2 * (1.0f / 64.0f) + EPS);
; #pragma unroll
;                     for (int bj = 0; bj < 2; ++bj)
; #pragma unroll
;                         for (int n = 0; n < 2; ++n) v[bj][n] = v[bj][n] * rn * gv[bj][n];
;                     int b, t; row_bt(r, b, t);
; #pragma unroll
;                     for (int n = 0; n < 2; ++n) {
;                         f32x4 o; o[0] = __shfl_xor(v[0][n][0], 16); o[1] = __shfl_xor(v[0][n][1], 16); o[2] = __shfl_xor(v[0][n][2], 16); o[3] = __shfl_xor(v[0][n][3], 16);
;                         f32x4 c, s;
; #pragma unroll
;                         for (int i = 0; i < 4; ++i) {
;                             const float angf = (float)t * ROPE_INV[4 * n + i];
;                             const float pr_ = angf * 0.15915494f, er_ = __builtin_fmaf(angf, 0.15915494f, -pr_);
;                             const float rev = __builtin_amdgcn_fractf(pr_) + __builtin_fmaf(angf, (float)(0.15915494309189535 - (double)0.15915494f), er_);
;                             c[i] = __builtin_amdgcn_cosf(rev); s[i] = __builtin_amdgcn_sinf(rev); }
;                         v[0][n] = (fq == 0) ? (v[0][n] * c - o * s) : ((fq == 1) ? (v[0][n] * c + o * s) : v[0][n]);
;                     }
; #pragma unroll
;                     for (int bj = 0; bj < 2; ++bj)
; #pragma unroll
;                         for (int n = 0; n < 2; ++n) v[bj][n] = v[bj][n] * qs;
;                 }
.LBB0_241:
	v_mov_b64_e32 v[106:107], s[16:17]
	v_mad_i64_i32 v[106:107], s[10:11], v142, s33, v[106:107]
	v_cvt_pk_bf16_f32 v108, v114, v115
	ds_read_b32 v114, v226 offset:192
	v_lshl_add_u64 v[106:107], s[8:9], 1, v[106:107]
	v_lshl_add_u64 v[106:107], v[106:107], 0, s[6:7]
	v_lshl_add_u64 v[110:111], v[106:107], 0, v[0:1]
	v_cvt_pk_bf16_f32 v106, v126, v127
	v_cvt_pk_bf16_f32 v107, v128, v129
	v_cvt_pk_bf16_f32 v109, v132, v133
	global_store_dwordx4 v[110:111], v[106:109], off
	s_waitcnt lgkmcnt(0)
	v_pk_mul_f32 v[112:113], v[104:105], v[114:115] op_sel_hi:[1,0]
	v_pk_mul_f32 v[98:99], v[98:99], v[114:115] op_sel_hi:[1,0]
	v_cvt_pk_bf16_f32 v106, v122, v123
	v_cvt_pk_bf16_f32 v107, v116, v117
	v_cvt_pk_bf16_f32 v108, v120, v121
	v_cvt_pk_bf16_f32 v109, v118, v119
	global_store_dwordx4 v[110:111], v[106:109], off offset:64
	v_pk_mul_f32 v[110:111], v[102:103], v[114:115] op_sel_hi:[1,0]
	v_pk_mul_f32 v[116:117], v[100:101], v[114:115] op_sel_hi:[1,0]
	v_pk_mul_f32 v[100:101], v[96:97], v[114:115] op_sel_hi:[1,0]
	v_pk_mul_f32 v[106:107], v[94:95], v[114:115] op_sel_hi:[1,0]
	v_pk_mul_f32 v[102:103], v[92:93], v[114:115] op_sel_hi:[1,0]
	v_pk_mul_f32 v[104:105], v[90:91], v[114:115] op_sel_hi:[1,0]
	s_and_b64 vcc, exec, s[40:41]
	v_add_u32_e32 v126, s2, v211
	s_cbranch_vccnz .LBB0_255
	v_pk_mul_f32 v[90:91], v[112:113], v[112:113]
	v_pk_mul_f32 v[92:93], v[110:111], v[110:111]
	s_mov_b32 s3, 0x800000
	v_pk_mov_b32 v[94:95], v[92:93], v[90:91] op_sel:[1,0]
	v_mov_b32_e32 v93, v91
	v_pk_add_f32 v[90:91], v[94:95], v[92:93]
	v_pk_mul_f32 v[92:93], v[116:117], v[116:117]
	v_pk_add_f32 v[90:91], v[90:91], v[90:91] op_sel_hi:[0,1]
	v_pk_mul_f32 v[94:95], v[98:99], v[98:99]
	v_mul_f32_e32 v90, v106, v106
	v_pk_mov_b32 v[96:97], v[94:95], v[92:93] op_sel:[1,0]
	v_mov_b32_e32 v95, v93
	v_pk_add_f32 v[92:93], v[96:97], v[94:95]
	v_pk_fma_f32 v[94:95], v[106:107], v[106:107], v[90:91] op_sel_hi:[1,1,0]
	v_mul_f32_e32 v90, v100, v100
	v_pk_add_f32 v[92:93], v[92:93], v[92:93] op_sel_hi:[0,1]
	v_pk_fma_f32 v[96:97], v[100:101], v[100:101], v[90:91] op_sel_hi:[1,1,0]
	v_mul_f32_e32 v94, v104, v104
	v_mul_f32_e32 v96, v105, v105
	v_mul_f32_e32 v90, v102, v102
	v_mul_f32_e32 v92, v103, v103
	v_pk_add_f32 v[94:95], v[94:95], v[96:97]
	v_pk_add_f32 v[90:91], v[90:91], v[92:93]
	s_nop 0
	v_pk_add_f32 v[90:91], v[94:95], v[90:91]
	s_nop 0
	v_add_f32_e32 v90, v90, v91
	ds_bpermute_b32 v91, v207, v90
	s_waitcnt lgkmcnt(0)
	v_add_f32_e32 v90, v90, v91
	ds_bpermute_b32 v91, v208, v90
	s_waitcnt lgkmcnt(0)
	v_add_f32_e32 v90, v90, v91
	v_fmamk_f32 v90, v90, 0x3c800000, v214
	v_mul_f32_e32 v91, 0x4b800000, v90
	v_cmp_gt_f32_e32 vcc, s3, v90
	s_nop 1
	v_cndmask_b32_e32 v90, v90, v91, vcc
	v_rsq_f32_e32 v90, v90
	s_nop 0
	v_mul_f32_e32 v91, 0x45800000, v90
	v_cndmask_b32_e32 v108, v90, v91, vcc
	v_mov_b32_e32 v109, v108
	v_pk_mul_f32 v[92:93], v[112:113], v[108:109] op_sel_hi:[1,0]
	v_pk_mul_f32 v[90:91], v[110:111], v[108:109] op_sel_hi:[1,0]
	s_nop 0
	v_pk_mul_f32 v[112:113], v[56:57], v[92:93]
	v_mul_hi_i32 v92, v126, s27
	v_lshrrev_b32_e32 v93, 31, v92
	v_ashrrev_i32_e32 v92, 12, v92
	v_add_u32_e32 v92, v92, v93
	v_mul_i32_i24_e32 v92, 0x2010, v92
	v_sub_u32_e32 v92, v126, v92
	v_cvt_f32_i32_e32 v125, v92
	v_pk_mul_f32 v[110:111], v[54:55], v[90:91]
	ds_bpermute_b32 v90, v207, v110
	ds_bpermute_b32 v91, v207, v111
	v_mul_f32_e32 v92, 0.15915494, v125
	v_fma_f32 v93, v125, 0.15915494, -v92
	v_fract_f32_e32 v92, v92
	v_fmac_f32_e32 v93, 0x31dc9c88, v125
	v_add_f32_e32 v92, v92, v93
	v_mul_f32_e32 v93, 0x3e4693af, v125
	v_mul_f32_e32 v95, 0.15915494, v93
	v_fma_f32 v96, v93, 0.15915494, -v95
	v_fract_f32_e32 v95, v95
	v_fmac_f32_e32 v96, 0x31dc9c88, v93
	v_add_f32_e32 v93, v95, v96
	v_mul_f32_e32 v96, 0x3d1a08c8, v125
	v_mul_f32_e32 v97, 0.15915494, v96
	v_fma_f32 v120, v96, 0.15915494, -v97
	v_fract_f32_e32 v97, v97
	v_fmac_f32_e32 v120, 0x31dc9c88, v96
	v_add_f32_e32 v96, v97, v120
	v_cos_f32_e32 v120, v96
	v_sin_f32_e32 v122, v96
	v_mul_f32_e32 v96, 0x3beef74e, v125
	v_mul_f32_e32 v97, 0.15915494, v96
	v_fma_f32 v121, v96, 0.15915494, -v97
	v_fract_f32_e32 v97, v97
	v_fmac_f32_e32 v121, 0x31dc9c88, v96
	ds_bpermute_b32 v118, v207, v112
	ds_bpermute_b32 v119, v207, v113
	v_add_f32_e32 v96, v97, v121
	v_cos_f32_e32 v94, v92
	v_sin_f32_e32 v92, v92
	v_cos_f32_e32 v95, v93
	v_sin_f32_e32 v93, v93
	v_cos_f32_e32 v121, v96
	v_sin_f32_e32 v123, v96
	v_mov_b32_e32 v114, v108
	v_mov_b32_e32 v115, v108
	v_cmp_lt_i32_e32 vcc, 0, v202
	s_and_saveexec_b64 s[10:11], vcc
	s_xor_b64 s[10:11], exec, s[10:11]
	s_cbranch_execz .LBB0_246
	v_cmp_eq_u32_e32 vcc, 1, v202
	s_and_saveexec_b64 s[14:15], vcc
	s_cbranch_execz .LBB0_245
	v_pk_mul_f32 v[96:97], v[120:121], v[112:113]
	v_pk_mul_f32 v[94:95], v[94:95], v[110:111]
	s_waitcnt lgkmcnt(0)
	v_pk_fma_f32 v[112:113], v[122:123], v[118:119], v[96:97]
	v_pk_fma_f32 v[110:111], v[92:93], v[90:91], v[94:95]

;     __device__ __forceinline__ void run(const f32x4 (&acc)[2][2][4][2], const Unit& u, int wr, int wc, int fr, int fq, const int nai, LAS unsigned char* lds, const int ui) const {
;     ...
;             for (int m = 0; m < 4; ++m) {
;                 const int r = u.pm * 256 + ai * 128 + wr * 64 + m * 16 + fr;
;                 const float rs = RT[ai * 128 + wr * 64 + m * 16 + fr];
;                 f32x4 v[2][2];
; #pragma unroll
;                 for (int bj = 0; bj < 2; ++bj)
; #pragma unroll
;                     for (int n = 0; n < 2; ++n) v[bj][n] = acc[ai][bj][m][n] * rs;
;                 if (isqk) {
;                     float q2 = 0.f;
; #pragma unroll
;                     for (int bj = 0; bj < 2; ++bj)
; #pragma unroll
;                         for (int n = 0; n < 2; ++n) { const f32x4 x = v[bj][n]; q2 += (x[0] * x[0] + x[1] * x[1]) + (x[2] * x[2] + x[3] * x[3]); }
;                     q2 += __shfl_xor(q2, 16); q2 += __shfl_xor(q2, 32);
;                     const float rn = rsqrtf(q2 * (1.0f / 64.0f) + EPS);
; #pragma unroll
;                     for (int bj = 0; bj < 2; ++bj)
; #pragma unroll
;                         for (int n = 0; n < 2; ++n) v[bj][n] = v[bj][n] * rn * gv[bj][n];
;                     int b, t; row_bt(r, b, t);
; #pragma unroll
;                     for (int n = 0; n < 2; ++n) {
;                         f32x4 o; o[0] = __shfl_xor(v[0][n][0], 16); o[1] = __shfl_xor(v[0][n][1], 16); o[2] = __shfl_xor(v[0][n][2], 16); o[3] = __shfl_xor(v[0][n][3], 16);
;                         f32x4 c, s;
; #pragma unroll
;                         for (int i = 0; i < 4; ++i) {
;                             const float angf = (float)t * ROPE_INV[4 * n + i];
;                             const float pr_ = angf * 0.15915494f, er_ = __builtin_fmaf(angf, 0.15915494f, -pr_);
;                             const float rev = __builtin_amdgcn_fractf(pr_) + __builtin_fmaf(angf, (float)(0.15915494309189535 - (double)0.15915494f), er_);
;                             c[i] = __builtin_amdgcn_cosf(rev); s[i] = __builtin_amdgcn_sinf(rev); }
;                         v[0][n] = (fq == 0) ? (v[0][n] * c - o * s) : ((fq == 1) ? (v[0][n] * c + o * s) : v[0][n]);
;                     }
; #pragma unroll
;                     for (int bj = 0; bj < 2; ++bj)
; #pragma unroll
;                         for (int n = 0; n < 2; ++n) v[bj][n] = v[bj][n] * qs;
;                 }
.LBB0_255:
	v_mov_b64_e32 v[90:91], s[16:17]
	v_mad_i64_i32 v[90:91], s[10:11], v126, s33, v[90:91]
	v_cvt_pk_bf16_f32 v92, v98, v99
	ds_read_b32 v98, v226 offset:512
	v_lshl_add_u64 v[90:91], s[8:9], 1, v[90:91]
	v_lshl_add_u64 v[90:91], v[90:91], 0, s[6:7]
	v_lshl_add_u64 v[94:95], v[90:91], 0, v[0:1]
	v_cvt_pk_bf16_f32 v90, v110, v111
	v_cvt_pk_bf16_f32 v91, v112, v113
	v_cvt_pk_bf16_f32 v93, v116, v117
	global_store_dwordx4 v[94:95], v[90:93], off
	s_waitcnt lgkmcnt(0)
	v_pk_mul_f32 v[96:97], v[88:89], v[98:99] op_sel_hi:[1,0]
	v_pk_mul_f32 v[82:83], v[82:83], v[98:99] op_sel_hi:[1,0]
	v_cvt_pk_bf16_f32 v90, v106, v107
	v_cvt_pk_bf16_f32 v91, v100, v101
	v_cvt_pk_bf16_f32 v92, v104, v105
	v_cvt_pk_bf16_f32 v93, v102, v103
	global_store_dwordx4 v[94:95], v[90:93], off offset:64
	v_pk_mul_f32 v[94:95], v[86:87], v[98:99] op_sel_hi:[1,0]
	v_pk_mul_f32 v[100:101], v[84:85], v[98:99] op_sel_hi:[1,0]
	v_pk_mul_f32 v[84:85], v[80:81], v[98:99] op_sel_hi:[1,0]
	v_pk_mul_f32 v[90:91], v[78:79], v[98:99] op_sel_hi:[1,0]
	v_pk_mul_f32 v[86:87], v[76:77], v[98:99] op_sel_hi:[1,0]
	v_pk_mul_f32 v[88:89], v[74:75], v[98:99] op_sel_hi:[1,0]
	s_and_b64 vcc, exec, s[40:41]
	v_add_u32_e32 v110, s2, v221
	s_cbranch_vccnz .LBB0_269
	v_pk_mul_f32 v[74:75], v[96:97], v[96:97]
	v_pk_mul_f32 v[76:77], v[94:95], v[94:95]
	s_mov_b32 s3, 0x800000
	v_pk_mov_b32 v[78:79], v[76:77], v[74:75] op_sel:[1,0]
	v_mov_b32_e32 v77, v75
	v_pk_add_f32 v[74:75], v[78:79], v[76:77]
	v_pk_mul_f32 v[76:77], v[100:101], v[100:101]
	v_pk_add_f32 v[74:75], v[74:75], v[74:75] op_sel_hi:[0,1]
	v_pk_mul_f32 v[78:79], v[82:83], v[82:83]
	v_mul_f32_e32 v74, v90, v90
	v_pk_mov_b32 v[80:81], v[78:79], v[76:77] op_sel:[1,0]
	v_mov_b32_e32 v79, v77
	v_pk_add_f32 v[76:77], v[80:81], v[78:79]
	v_pk_fma_f32 v[78:79], v[90:91], v[90:91], v[74:75] op_sel_hi:[1,1,0]
	v_mul_f32_e32 v74, v84, v84
	v_pk_add_f32 v[76:77], v[76:77], v[76:77] op_sel_hi:[0,1]
	v_pk_fma_f32 v[80:81], v[84:85], v[84:85], v[74:75] op_sel_hi:[1,1,0]
	v_mul_f32_e32 v78, v88, v88
	v_mul_f32_e32 v80, v89, v89
	v_mul_f32_e32 v74, v86, v86
	v_mul_f32_e32 v76, v87, v87
	v_pk_add_f32 v[78:79], v[78:79], v[80:81]
	v_pk_add_f32 v[74:75], v[74:75], v[76:77]
	s_nop 0
	v_pk_add_f32 v[74:75], v[78:79], v[74:75]
	s_nop 0
	v_add_f32_e32 v74, v74, v75
	ds_bpermute_b32 v75, v207, v74
	s_waitcnt lgkmcnt(0)
	v_add_f32_e32 v74, v74, v75
	ds_bpermute_b32 v75, v208, v74
	s_waitcnt lgkmcnt(0)
	v_add_f32_e32 v74, v74, v75
	v_fmamk_f32 v74, v74, 0x3c800000, v214
	v_mul_f32_e32 v75, 0x4b800000, v74
	v_cmp_gt_f32_e32 vcc, s3, v74
	s_nop 1
	v_cndmask_b32_e32 v74, v74, v75, vcc
	v_rsq_f32_e32 v74, v74
	s_nop 0
	v_mul_f32_e32 v75, 0x45800000, v74
	v_cndmask_b32_e32 v92, v74, v75, vcc
	v_mov_b32_e32 v93, v92
	v_pk_mul_f32 v[76:77], v[96:97], v[92:93] op_sel_hi:[1,0]
	v_pk_mul_f32 v[74:75], v[94:95], v[92:93] op_sel_hi:[1,0]
	s_nop 0
	v_pk_mul_f32 v[96:97], v[56:57], v[76:77]
	v_mul_hi_i32 v76, v110, s27
	v_lshrrev_b32_e32 v77, 31, v76
	v_ashrrev_i32_e32 v76, 12, v76
	v_add_u32_e32 v76, v76, v77
	v_mul_i32_i24_e32 v76, 0x2010, v76
	v_sub_u32_e32 v76, v110, v76
	v_cvt_f32_i32_e32 v109, v76
	v_pk_mul_f32 v[94:95], v[54:55], v[74:75]
	ds_bpermute_b32 v74, v207, v94
	ds_bpermute_b32 v75, v207, v95
	v_mul_f32_e32 v76, 0.15915494, v109
	v_fma_f32 v77, v109, 0.15915494, -v76
	v_fract_f32_e32 v76, v76
	v_fmac_f32_e32 v77, 0x31dc9c88, v109
	v_add_f32_e32 v76, v76, v77
	v_mul_f32_e32 v77, 0x3e4693af, v109
	v_mul_f32_e32 v79, 0.15915494, v77
	v_fma_f32 v80, v77, 0.15915494, -v79
	v_fract_f32_e32 v79, v79
	v_fmac_f32_e32 v80, 0x31dc9c88, v77
	v_add_f32_e32 v77, v79, v80
	v_mul_f32_e32 v80, 0x3d1a08c8, v109
	v_mul_f32_e32 v81, 0.15915494, v80
	v_fma_f32 v104, v80, 0.15915494, -v81
	v_fract_f32_e32 v81, v81
	v_fmac_f32_e32 v104, 0x31dc9c88, v80
	v_add_f32_e32 v80, v81, v104
	v_cos_f32_e32 v104, v80
	v_sin_f32_e32 v106, v80
	v_mul_f32_e32 v80, 0x3beef74e, v109
	v_mul_f32_e32 v81, 0.15915494, v80
	v_fma_f32 v105, v80, 0.15915494, -v81
	v_fract_f32_e32 v81, v81
	v_fmac_f32_e32 v105, 0x31dc9c88, v80
	ds_bpermute_b32 v102, v207, v96
	ds_bpermute_b32 v103, v207, v97
	v_add_f32_e32 v80, v81, v105
	v_cos_f32_e32 v78, v76
	v_sin_f32_e32 v76, v76
	v_cos_f32_e32 v79, v77
	v_sin_f32_e32 v77, v77
	v_cos_f32_e32 v105, v80
	v_sin_f32_e32 v107, v80
	v_mov_b32_e32 v98, v92
	v_mov_b32_e32 v99, v92
	v_cmp_lt_i32_e32 vcc, 0, v202
	s_and_saveexec_b64 s[10:11], vcc
	s_xor_b64 s[10:11], exec, s[10:11]
	s_cbranch_execz .LBB0_260
	v_cmp_eq_u32_e32 vcc, 1, v202
	s_and_saveexec_b64 s[14:15], vcc
	s_cbranch_execz .LBB0_259
	v_pk_mul_f32 v[80:81], v[104:105], v[96:97]
	v_pk_mul_f32 v[78:79], v[78:79], v[94:95]
	s_waitcnt lgkmcnt(0)
	v_pk_fma_f32 v[96:97], v[106:107], v[102:103], v[80:81]
	v_pk_fma_f32 v[94:95], v[76:77], v[74:75], v[78:79]

;     __device__ __forceinline__ void run(const f32x4 (&acc)[2][2][4][2], const Unit& u, int wr, int wc, int fr, int fq, const int nai, LAS unsigned char* lds, const int ui) const {
;     ...
;             for (int m = 0; m < 4; ++m) {
;                 const int r = u.pm * 256 + ai * 128 + wr * 64 + m * 16 + fr;
;                 const float rs = RT[ai * 128 + wr * 64 + m * 16 + fr];
;                 f32x4 v[2][2];
; #pragma unroll
;                 for (int bj = 0; bj < 2; ++bj)
; #pragma unroll
;                     for (int n = 0; n < 2; ++n) v[bj][n] = acc[ai][bj][m][n] * rs;
;                 if (isqk) {
;                     float q2 = 0.f;
; #pragma unroll
;                     for (int bj = 0; bj < 2; ++bj)
; #pragma unroll
;                         for (int n = 0; n < 2; ++n) { const f32x4 x = v[bj][n]; q2 += (x[0] * x[0] + x[1] * x[1]) + (x[2] * x[2] + x[3] * x[3]); }
;                     q2 += __shfl_xor(q2, 16); q2 += __shfl_xor(q2, 32);
;                     const float rn = rsqrtf(q2 * (1.0f / 64.0f) + EPS);
; #pragma unroll
;                     for (int bj = 0; bj < 2; ++bj)
; #pragma unroll
;                         for (int n = 0; n < 2; ++n) v[bj][n] = v[bj][n] * rn * gv[bj][n];
;                     int b, t; row_bt(r, b, t);
; #pragma unroll
;                     for (int n = 0; n < 2; ++n) {
;                         f32x4 o; o[0] = __shfl_xor(v[0][n][0], 16); o[1] = __shfl_xor(v[0][n][1], 16); o[2] = __shfl_xor(v[0][n][2], 16); o[3] = __shfl_xor(v[0][n][3], 16);
;                         f32x4 c, s;
; #pragma unroll
;                         for (int i = 0; i < 4; ++i) {
;                             const float angf = (float)t * ROPE_INV[4 * n + i];
;                             const float pr_ = angf * 0.15915494f, er_ = __builtin_fmaf(angf, 0.15915494f, -pr_);
;                             const float rev = __builtin_amdgcn_fractf(pr_) + __builtin_fmaf(angf, (float)(0.15915494309189535 - (double)0.15915494f), er_);
;                             c[i] = __builtin_amdgcn_cosf(rev); s[i] = __builtin_amdgcn_sinf(rev); }
;                         v[0][n] = (fq == 0) ? (v[0][n] * c - o * s) : ((fq == 1) ? (v[0][n] * c + o * s) : v[0][n]);
;                     }
; #pragma unroll
;                     for (int bj = 0; bj < 2; ++bj)
; #pragma unroll
;                         for (int n = 0; n < 2; ++n) v[bj][n] = v[bj][n] * qs;
;                 }
.LBB0_269:
	v_mov_b64_e32 v[74:75], s[16:17]
	v_mad_i64_i32 v[74:75], s[10:11], v110, s33, v[74:75]
	v_cvt_pk_bf16_f32 v76, v82, v83
	ds_read_b32 v82, v226 offset:576
	v_lshl_add_u64 v[74:75], s[8:9], 1, v[74:75]
	v_lshl_add_u64 v[74:75], v[74:75], 0, s[6:7]
	v_lshl_add_u64 v[78:79], v[74:75], 0, v[0:1]
	v_cvt_pk_bf16_f32 v74, v94, v95
	v_cvt_pk_bf16_f32 v75, v96, v97
	v_cvt_pk_bf16_f32 v77, v100, v101
	global_store_dwordx4 v[78:79], v[74:77], off
	s_waitcnt lgkmcnt(0)
	v_pk_mul_f32 v[80:81], v[72:73], v[82:83] op_sel_hi:[1,0]
	v_pk_mul_f32 v[66:67], v[66:67], v[82:83] op_sel_hi:[1,0]
	v_cvt_pk_bf16_f32 v74, v90, v91
	v_cvt_pk_bf16_f32 v75, v84, v85
	v_cvt_pk_bf16_f32 v76, v88, v89
	v_cvt_pk_bf16_f32 v77, v86, v87
	global_store_dwordx4 v[78:79], v[74:77], off offset:64
	v_pk_mul_f32 v[78:79], v[70:71], v[82:83] op_sel_hi:[1,0]
	v_pk_mul_f32 v[84:85], v[68:69], v[82:83] op_sel_hi:[1,0]
	v_pk_mul_f32 v[68:69], v[64:65], v[82:83] op_sel_hi:[1,0]
	v_pk_mul_f32 v[74:75], v[62:63], v[82:83] op_sel_hi:[1,0]
	v_pk_mul_f32 v[70:71], v[60:61], v[82:83] op_sel_hi:[1,0]
	v_pk_mul_f32 v[72:73], v[58:59], v[82:83] op_sel_hi:[1,0]
	s_and_b64 vcc, exec, s[40:41]
	v_add_u32_e32 v94, s2, v222
	s_cbranch_vccnz .LBB0_283
	v_pk_mul_f32 v[58:59], v[80:81], v[80:81]
	v_pk_mul_f32 v[60:61], v[78:79], v[78:79]
	s_mov_b32 s3, 0x800000
	v_pk_mov_b32 v[62:63], v[60:61], v[58:59] op_sel:[1,0]
	v_mov_b32_e32 v61, v59
	v_pk_add_f32 v[58:59], v[62:63], v[60:61]
	v_pk_mul_f32 v[60:61], v[84:85], v[84:85]
	v_pk_add_f32 v[58:59], v[58:59], v[58:59] op_sel_hi:[0,1]
	v_pk_mul_f32 v[62:63], v[66:67], v[66:67]
	v_mul_f32_e32 v58, v74, v74
	v_pk_mov_b32 v[64:65], v[62:63], v[60:61] op_sel:[1,0]
	v_mov_b32_e32 v63, v61
	v_pk_add_f32 v[60:61], v[64:65], v[62:63]
	v_pk_fma_f32 v[62:63], v[74:75], v[74:75], v[58:59] op_sel_hi:[1,1,0]
	v_mul_f32_e32 v58, v68, v68
	v_pk_add_f32 v[60:61], v[60:61], v[60:61] op_sel_hi:[0,1]
	v_pk_fma_f32 v[64:65], v[68:69], v[68:69], v[58:59] op_sel_hi:[1,1,0]
	v_mul_f32_e32 v62, v72, v72
	v_mul_f32_e32 v64, v73, v73
	v_mul_f32_e32 v58, v70, v70
	v_mul_f32_e32 v60, v71, v71
	v_pk_add_f32 v[62:63], v[62:63], v[64:65]
	v_pk_add_f32 v[58:59], v[58:59], v[60:61]
	s_nop 0
	v_pk_add_f32 v[58:59], v[62:63], v[58:59]
	s_nop 0
	v_add_f32_e32 v58, v58, v59
	ds_bpermute_b32 v59, v207, v58
	s_waitcnt lgkmcnt(0)
	v_add_f32_e32 v58, v58, v59
	ds_bpermute_b32 v59, v208, v58
	s_waitcnt lgkmcnt(0)
	v_add_f32_e32 v58, v58, v59
	v_fmamk_f32 v58, v58, 0x3c800000, v214
	v_mul_f32_e32 v59, 0x4b800000, v58
	v_cmp_gt_f32_e32 vcc, s3, v58
	s_nop 1
	v_cndmask_b32_e32 v58, v58, v59, vcc
	v_rsq_f32_e32 v58, v58
	s_nop 0
	v_mul_f32_e32 v59, 0x45800000, v58
	v_cndmask_b32_e32 v76, v58, v59, vcc
	v_mov_b32_e32 v77, v76
	v_pk_mul_f32 v[60:61], v[80:81], v[76:77] op_sel_hi:[1,0]
	v_pk_mul_f32 v[58:59], v[78:79], v[76:77] op_sel_hi:[1,0]
	s_nop 0
	v_pk_mul_f32 v[80:81], v[56:57], v[60:61]
	v_mul_hi_i32 v60, v94, s27
	v_lshrrev_b32_e32 v61, 31, v60
	v_ashrrev_i32_e32 v60, 12, v60
	v_add_u32_e32 v60, v60, v61
	v_mul_i32_i24_e32 v60, 0x2010, v60
	v_sub_u32_e32 v60, v94, v60
	v_cvt_f32_i32_e32 v93, v60
	v_pk_mul_f32 v[78:79], v[54:55], v[58:59]
	ds_bpermute_b32 v58, v207, v78
	ds_bpermute_b32 v59, v207, v79
	v_mul_f32_e32 v60, 0.15915494, v93
	v_fma_f32 v61, v93, 0.15915494, -v60
	v_fract_f32_e32 v60, v60
	v_fmac_f32_e32 v61, 0x31dc9c88, v93
	v_add_f32_e32 v60, v60, v61
	v_mul_f32_e32 v61, 0x3e4693af, v93
	v_mul_f32_e32 v63, 0.15915494, v61
	v_fma_f32 v64, v61, 0.15915494, -v63
	v_fract_f32_e32 v63, v63
	v_fmac_f32_e32 v64, 0x31dc9c88, v61
	v_add_f32_e32 v61, v63, v64
	v_mul_f32_e32 v64, 0x3d1a08c8, v93
	v_mul_f32_e32 v65, 0.15915494, v64
	v_fma_f32 v88, v64, 0.15915494, -v65
	v_fract_f32_e32 v65, v65
	v_fmac_f32_e32 v88, 0x31dc9c88, v64
	v_add_f32_e32 v64, v65, v88
	v_cos_f32_e32 v88, v64
	v_sin_f32_e32 v90, v64
	v_mul_f32_e32 v64, 0x3beef74e, v93
	v_mul_f32_e32 v65, 0.15915494, v64
	v_fma_f32 v89, v64, 0.15915494, -v65
	v_fract_f32_e32 v65, v65
	v_fmac_f32_e32 v89, 0x31dc9c88, v64
	ds_bpermute_b32 v86, v207, v80
	ds_bpermute_b32 v87, v207, v81
	v_add_f32_e32 v64, v65, v89
	v_cos_f32_e32 v62, v60
	v_sin_f32_e32 v60, v60
	v_cos_f32_e32 v63, v61
	v_sin_f32_e32 v61, v61
	v_cos_f32_e32 v89, v64
	v_sin_f32_e32 v91, v64
	v_mov_b32_e32 v82, v76
	v_mov_b32_e32 v83, v76
	v_cmp_lt_i32_e32 vcc, 0, v202
	s_and_saveexec_b64 s[10:11], vcc
	s_xor_b64 s[10:11], exec, s[10:11]
	s_cbranch_execz .LBB0_274
	v_cmp_eq_u32_e32 vcc, 1, v202
	s_and_saveexec_b64 s[14:15], vcc
	s_cbranch_execz .LBB0_273
	v_pk_mul_f32 v[64:65], v[88:89], v[80:81]
	v_pk_mul_f32 v[62:63], v[62:63], v[78:79]
	s_waitcnt lgkmcnt(0)
	v_pk_fma_f32 v[80:81], v[90:91], v[86:87], v[64:65]
	v_pk_fma_f32 v[78:79], v[60:61], v[58:59], v[62:63]

;     __device__ __forceinline__ void run(const f32x4 (&acc)[2][2][4][2], const Unit& u, int wr, int wc, int fr, int fq, const int nai, LAS unsigned char* lds, const int ui) const {
;     ...
;             for (int m = 0; m < 4; ++m) {
;                 const int r = u.pm * 256 + ai * 128 + wr * 64 + m * 16 + fr;
;                 const float rs = RT[ai * 128 + wr * 64 + m * 16 + fr];
;                 f32x4 v[2][2];
; #pragma unroll
;                 for (int bj = 0; bj < 2; ++bj)
; #pragma unroll
;                     for (int n = 0; n < 2; ++n) v[bj][n] = acc[ai][bj][m][n] * rs;
;                 if (isqk) {
;                     float q2 = 0.f;
; #pragma unroll
;                     for (int bj = 0; bj < 2; ++bj)
; #pragma unroll
;                         for (int n = 0; n < 2; ++n) { const f32x4 x = v[bj][n]; q2 += (x[0] * x[0] + x[1] * x[1]) + (x[2] * x[2] + x[3] * x[3]); }
;                     q2 += __shfl_xor(q2, 16); q2 += __shfl_xor(q2, 32);
;                     const float rn = rsqrtf(q2 * (1.0f / 64.0f) + EPS);
; #pragma unroll
;                     for (int bj = 0; bj < 2; ++bj)
; #pragma unroll
;                         for (int n = 0; n < 2; ++n) v[bj][n] = v[bj][n] * rn * gv[bj][n];
;                     int b, t; row_bt(r, b, t);
; #pragma unroll
;                     for (int n = 0; n < 2; ++n) {
;                         f32x4 o; o[0] = __shfl_xor(v[0][n][0], 16); o[1] = __shfl_xor(v[0][n][1], 16); o[2] = __shfl_xor(v[0][n][2], 16); o[3] = __shfl_xor(v[0][n][3], 16);
;                         f32x4 c, s;
; #pragma unroll
;                         for (int i = 0; i < 4; ++i) {
;                             const float angf = (float)t * ROPE_INV[4 * n + i];
;                             const float pr_ = angf * 0.15915494f, er_ = __builtin_fmaf(angf, 0.15915494f, -pr_);
;                             const float rev = __builtin_amdgcn_fractf(pr_) + __builtin_fmaf(angf, (float)(0.15915494309189535 - (double)0.15915494f), er_);
;                             c[i] = __builtin_amdgcn_cosf(rev); s[i] = __builtin_amdgcn_sinf(rev); }
;                         v[0][n] = (fq == 0) ? (v[0][n] * c - o * s) : ((fq == 1) ? (v[0][n] * c + o * s) : v[0][n]);
;                     }
; #pragma unroll
;                     for (int bj = 0; bj < 2; ++bj)
; #pragma unroll
;                         for (int n = 0; n < 2; ++n) v[bj][n] = v[bj][n] * qs;
;                 }
.LBB0_283:
	v_mov_b64_e32 v[58:59], s[16:17]
	v_mad_i64_i32 v[58:59], s[10:11], v94, s33, v[58:59]
	v_cvt_pk_bf16_f32 v60, v66, v67
	ds_read_b32 v66, v226 offset:640
	v_lshl_add_u64 v[58:59], s[8:9], 1, v[58:59]
	v_lshl_add_u64 v[58:59], v[58:59], 0, s[6:7]
	v_lshl_add_u64 v[62:63], v[58:59], 0, v[0:1]
	v_cvt_pk_bf16_f32 v58, v78, v79
	v_cvt_pk_bf16_f32 v59, v80, v81
	v_cvt_pk_bf16_f32 v61, v84, v85
	global_store_dwordx4 v[62:63], v[58:61], off
	s_waitcnt lgkmcnt(0)
	v_pk_mul_f32 v[64:65], v[52:53], v[66:67] op_sel_hi:[1,0]
	v_pk_mul_f32 v[42:43], v[42:43], v[66:67] op_sel_hi:[1,0]
	v_cvt_pk_bf16_f32 v58, v74, v75
	v_cvt_pk_bf16_f32 v59, v68, v69
	v_cvt_pk_bf16_f32 v60, v72, v73
	v_cvt_pk_bf16_f32 v61, v70, v71
	global_store_dwordx4 v[62:63], v[58:61], off offset:64
	v_pk_mul_f32 v[62:63], v[50:51], v[66:67] op_sel_hi:[1,0]
	v_pk_mul_f32 v[68:69], v[44:45], v[66:67] op_sel_hi:[1,0]
	v_pk_mul_f32 v[44:45], v[40:41], v[66:67] op_sel_hi:[1,0]
	v_pk_mul_f32 v[58:59], v[38:39], v[66:67] op_sel_hi:[1,0]
	v_pk_mul_f32 v[50:51], v[36:37], v[66:67] op_sel_hi:[1,0]
	v_pk_mul_f32 v[52:53], v[34:35], v[66:67] op_sel_hi:[1,0]
	s_and_b64 vcc, exec, s[40:41]
	v_add_u32_e32 v78, s2, v223
	s_cbranch_vccnz .LBB0_297
	v_pk_mul_f32 v[34:35], v[64:65], v[64:65]
	v_pk_mul_f32 v[36:37], v[62:63], v[62:63]
	s_mov_b32 s3, 0x800000
	v_pk_mov_b32 v[38:39], v[36:37], v[34:35] op_sel:[1,0]
	v_mov_b32_e32 v37, v35
	v_pk_add_f32 v[34:35], v[38:39], v[36:37]
	v_pk_mul_f32 v[36:37], v[68:69], v[68:69]
	v_pk_add_f32 v[34:35], v[34:35], v[34:35] op_sel_hi:[0,1]
	v_pk_mul_f32 v[38:39], v[42:43], v[42:43]
	v_mul_f32_e32 v34, v58, v58
	v_pk_mov_b32 v[40:41], v[38:39], v[36:37] op_sel:[1,0]
	v_mov_b32_e32 v39, v37
	v_pk_add_f32 v[36:37], v[40:41], v[38:39]
	v_pk_fma_f32 v[38:39], v[58:59], v[58:59], v[34:35] op_sel_hi:[1,1,0]
	v_mul_f32_e32 v34, v44, v44
	v_pk_add_f32 v[36:37], v[36:37], v[36:37] op_sel_hi:[0,1]
	v_pk_fma_f32 v[40:41], v[44:45], v[44:45], v[34:35] op_sel_hi:[1,1,0]
	v_mul_f32_e32 v38, v52, v52
	v_mul_f32_e32 v40, v53, v53
	v_mul_f32_e32 v34, v50, v50
	v_mul_f32_e32 v36, v51, v51
	v_pk_add_f32 v[38:39], v[38:39], v[40:41]
	v_pk_add_f32 v[34:35], v[34:35], v[36:37]
	s_nop 0
	v_pk_add_f32 v[34:35], v[38:39], v[34:35]
	s_nop 0
	v_add_f32_e32 v34, v34, v35
	ds_bpermute_b32 v35, v207, v34
	s_waitcnt lgkmcnt(0)
	v_add_f32_e32 v34, v34, v35
	ds_bpermute_b32 v35, v208, v34
	s_waitcnt lgkmcnt(0)
	v_add_f32_e32 v34, v34, v35
	v_fmamk_f32 v34, v34, 0x3c800000, v214
	v_mul_f32_e32 v35, 0x4b800000, v34
	v_cmp_gt_f32_e32 vcc, s3, v34
	s_nop 1
	v_cndmask_b32_e32 v34, v34, v35, vcc
	v_rsq_f32_e32 v34, v34
	s_nop 0
	v_mul_f32_e32 v35, 0x45800000, v34
	v_cndmask_b32_e32 v60, v34, v35, vcc
	v_mov_b32_e32 v61, v60
	v_pk_mul_f32 v[36:37], v[64:65], v[60:61] op_sel_hi:[1,0]
	v_pk_mul_f32 v[34:35], v[62:63], v[60:61] op_sel_hi:[1,0]
	s_nop 0
	v_pk_mul_f32 v[64:65], v[56:57], v[36:37]
	v_mul_hi_i32 v36, v78, s27
	v_lshrrev_b32_e32 v37, 31, v36
	v_ashrrev_i32_e32 v36, 12, v36
	v_add_u32_e32 v36, v36, v37
	v_mul_i32_i24_e32 v36, 0x2010, v36
	v_sub_u32_e32 v36, v78, v36
	v_cvt_f32_i32_e32 v77, v36
	v_pk_mul_f32 v[62:63], v[54:55], v[34:35]
	ds_bpermute_b32 v34, v207, v62
	ds_bpermute_b32 v35, v207, v63
	v_mul_f32_e32 v36, 0.15915494, v77
	v_fma_f32 v37, v77, 0.15915494, -v36
	v_fract_f32_e32 v36, v36
	v_fmac_f32_e32 v37, 0x31dc9c88, v77
	v_add_f32_e32 v36, v36, v37
	v_mul_f32_e32 v37, 0x3e4693af, v77
	v_mul_f32_e32 v39, 0.15915494, v37
	v_fma_f32 v40, v37, 0.15915494, -v39
	v_fract_f32_e32 v39, v39
	v_fmac_f32_e32 v40, 0x31dc9c88, v37
	v_add_f32_e32 v37, v39, v40
	v_mul_f32_e32 v40, 0x3d1a08c8, v77
	v_mul_f32_e32 v41, 0.15915494, v40
	v_fma_f32 v72, v40, 0.15915494, -v41
	v_fract_f32_e32 v41, v41
	v_fmac_f32_e32 v72, 0x31dc9c88, v40
	v_add_f32_e32 v40, v41, v72
	v_cos_f32_e32 v72, v40
	v_sin_f32_e32 v74, v40
	v_mul_f32_e32 v40, 0x3beef74e, v77
	v_mul_f32_e32 v41, 0.15915494, v40
	v_fma_f32 v73, v40, 0.15915494, -v41
	v_fract_f32_e32 v41, v41
	v_fmac_f32_e32 v73, 0x31dc9c88, v40
	ds_bpermute_b32 v70, v207, v64
	ds_bpermute_b32 v71, v207, v65
	v_add_f32_e32 v40, v41, v73
	v_cos_f32_e32 v38, v36
	v_sin_f32_e32 v36, v36
	v_cos_f32_e32 v39, v37
	v_sin_f32_e32 v37, v37
	v_cos_f32_e32 v73, v40
	v_sin_f32_e32 v75, v40
	v_mov_b32_e32 v66, v60
	v_mov_b32_e32 v67, v60
	v_cmp_lt_i32_e32 vcc, 0, v202
	s_and_saveexec_b64 s[10:11], vcc
	s_xor_b64 s[10:11], exec, s[10:11]
	s_cbranch_execz .LBB0_288
	v_cmp_eq_u32_e32 vcc, 1, v202
	s_and_saveexec_b64 s[14:15], vcc
	s_cbranch_execz .LBB0_287
	v_pk_mul_f32 v[40:41], v[72:73], v[64:65]
	v_pk_mul_f32 v[38:39], v[38:39], v[62:63]
	s_waitcnt lgkmcnt(0)
	v_pk_fma_f32 v[64:65], v[74:75], v[70:71], v[40:41]
	v_pk_fma_f32 v[62:63], v[36:37], v[34:35], v[38:39]

;     __device__ __forceinline__ void run(const f32x4 (&acc)[2][2][4][2], const Unit& u, int wr, int wc, int fr, int fq, const int nai, LAS unsigned char* lds, const int ui) const {
;     ...
;             for (int m = 0; m < 4; ++m) {
;                 const int r = u.pm * 256 + ai * 128 + wr * 64 + m * 16 + fr;
;                 const float rs = RT[ai * 128 + wr * 64 + m * 16 + fr];
;                 f32x4 v[2][2];
; #pragma unroll
;                 for (int bj = 0; bj < 2; ++bj)
; #pragma unroll
;                     for (int n = 0; n < 2; ++n) v[bj][n] = acc[ai][bj][m][n] * rs;
;                 if (isqk) {
;                     float q2 = 0.f;
; #pragma unroll
;                     for (int bj = 0; bj < 2; ++bj)
; #pragma unroll
;                         for (int n = 0; n < 2; ++n) { const f32x4 x = v[bj][n]; q2 += (x[0] * x[0] + x[1] * x[1]) + (x[2] * x[2] + x[3] * x[3]); }
;                     q2 += __shfl_xor(q2, 16); q2 += __shfl_xor(q2, 32);
;                     const float rn = rsqrtf(q2 * (1.0f / 64.0f) + EPS);
; #pragma unroll
;                     for (int bj = 0; bj < 2; ++bj)
; #pragma unroll
;                         for (int n = 0; n < 2; ++n) v[bj][n] = v[bj][n] * rn * gv[bj][n];
;                     int b, t; row_bt(r, b, t);
; #pragma unroll
;                     for (int n = 0; n < 2; ++n) {
;                         f32x4 o; o[0] = __shfl_xor(v[0][n][0], 16); o[1] = __shfl_xor(v[0][n][1], 16); o[2] = __shfl_xor(v[0][n][2], 16); o[3] = __shfl_xor(v[0][n][3], 16);
;                         f32x4 c, s;
; #pragma unroll
;                         for (int i = 0; i < 4; ++i) {
;                             const float angf = (float)t * ROPE_INV[4 * n + i];
;                             const float pr_ = angf * 0.15915494f, er_ = __builtin_fmaf(angf, 0.15915494f, -pr_);
;                             const float rev = __builtin_amdgcn_fractf(pr_) + __builtin_fmaf(angf, (float)(0.15915494309189535 - (double)0.15915494f), er_);
;                             c[i] = __builtin_amdgcn_cosf(rev); s[i] = __builtin_amdgcn_sinf(rev); }
;                         v[0][n] = (fq == 0) ? (v[0][n] * c - o * s) : ((fq == 1) ? (v[0][n] * c + o * s) : v[0][n]);
;                     }
; #pragma unroll
;                     for (int bj = 0; bj < 2; ++bj)
; #pragma unroll
;                         for (int n = 0; n < 2; ++n) v[bj][n] = v[bj][n] * qs;
;                 }
.LBB0_297:
	v_mov_b64_e32 v[34:35], s[16:17]
	v_mad_i64_i32 v[34:35], s[10:11], v78, s33, v[34:35]
	v_cvt_pk_bf16_f32 v36, v42, v43
	ds_read_b32 v42, v226 offset:704
	v_lshl_add_u64 v[34:35], s[8:9], 1, v[34:35]
	v_lshl_add_u64 v[34:35], v[34:35], 0, s[6:7]
	v_lshl_add_u64 v[38:39], v[34:35], 0, v[0:1]
	v_cvt_pk_bf16_f32 v34, v62, v63
	v_cvt_pk_bf16_f32 v35, v64, v65
	v_cvt_pk_bf16_f32 v37, v68, v69
	global_store_dwordx4 v[38:39], v[34:37], off
	s_waitcnt lgkmcnt(0)
	v_pk_mul_f32 v[40:41], v[16:17], v[42:43] op_sel_hi:[1,0]
	v_pk_mul_f32 v[10:11], v[10:11], v[42:43] op_sel_hi:[1,0]
	v_cvt_pk_bf16_f32 v34, v58, v59
	v_cvt_pk_bf16_f32 v35, v44, v45
	v_cvt_pk_bf16_f32 v36, v52, v53
	v_cvt_pk_bf16_f32 v37, v50, v51
	global_store_dwordx4 v[38:39], v[34:37], off offset:64
	v_pk_mul_f32 v[38:39], v[14:15], v[42:43] op_sel_hi:[1,0]
	v_pk_mul_f32 v[44:45], v[12:13], v[42:43] op_sel_hi:[1,0]
	v_pk_mul_f32 v[12:13], v[8:9], v[42:43] op_sel_hi:[1,0]
	v_pk_mul_f32 v[34:35], v[6:7], v[42:43] op_sel_hi:[1,0]
	v_pk_mul_f32 v[14:15], v[4:5], v[42:43] op_sel_hi:[1,0]
	v_pk_mul_f32 v[16:17], v[2:3], v[42:43] op_sel_hi:[1,0]
	s_and_b64 vcc, exec, s[40:41]
	v_add_u32_e32 v58, s2, v224
	s_cbranch_vccnz .LBB0_311
	v_pk_mul_f32 v[2:3], v[40:41], v[40:41]
	v_pk_mul_f32 v[4:5], v[38:39], v[38:39]
	s_mov_b32 s2, 0x800000
	v_pk_mov_b32 v[6:7], v[4:5], v[2:3] op_sel:[1,0]
	v_mov_b32_e32 v5, v3
	v_pk_add_f32 v[2:3], v[6:7], v[4:5]
	v_pk_mul_f32 v[4:5], v[44:45], v[44:45]
	v_pk_add_f32 v[2:3], v[2:3], v[2:3] op_sel_hi:[0,1]
	v_pk_mul_f32 v[6:7], v[10:11], v[10:11]
	v_mul_f32_e32 v2, v34, v34
	v_pk_mov_b32 v[8:9], v[6:7], v[4:5] op_sel:[1,0]
	v_mov_b32_e32 v7, v5
	v_pk_add_f32 v[4:5], v[8:9], v[6:7]
	v_pk_fma_f32 v[6:7], v[34:35], v[34:35], v[2:3] op_sel_hi:[1,1,0]
	v_mul_f32_e32 v2, v12, v12
	v_pk_add_f32 v[4:5], v[4:5], v[4:5] op_sel_hi:[0,1]
	v_pk_fma_f32 v[8:9], v[12:13], v[12:13], v[2:3] op_sel_hi:[1,1,0]
	v_mul_f32_e32 v6, v16, v16
	v_mul_f32_e32 v8, v17, v17
	v_mul_f32_e32 v2, v14, v14
	v_mul_f32_e32 v4, v15, v15
	v_pk_add_f32 v[6:7], v[6:7], v[8:9]
	v_pk_add_f32 v[2:3], v[2:3], v[4:5]
	s_nop 0
	v_pk_add_f32 v[2:3], v[6:7], v[2:3]
	s_nop 0
	v_add_f32_e32 v2, v2, v3
	ds_bpermute_b32 v3, v207, v2
	s_waitcnt lgkmcnt(0)
	v_add_f32_e32 v2, v2, v3
	ds_bpermute_b32 v3, v208, v2
	s_waitcnt lgkmcnt(0)
	v_add_f32_e32 v2, v2, v3
	v_fmamk_f32 v2, v2, 0x3c800000, v214
	v_mul_f32_e32 v3, 0x4b800000, v2
	v_cmp_gt_f32_e32 vcc, s2, v2
	s_nop 1
	v_cndmask_b32_e32 v2, v2, v3, vcc
	v_rsq_f32_e32 v2, v2
	s_nop 0
	v_mul_f32_e32 v3, 0x45800000, v2
	v_cndmask_b32_e32 v36, v2, v3, vcc
	v_mov_b32_e32 v37, v36
	v_pk_mul_f32 v[4:5], v[40:41], v[36:37] op_sel_hi:[1,0]
	v_pk_mul_f32 v[2:3], v[38:39], v[36:37] op_sel_hi:[1,0]
	s_nop 0
	v_pk_mul_f32 v[40:41], v[56:57], v[4:5]
	v_mul_hi_i32 v4, v58, s27
	v_lshrrev_b32_e32 v5, 31, v4
	v_ashrrev_i32_e32 v4, 12, v4
	v_add_u32_e32 v4, v4, v5
	v_mul_i32_i24_e32 v4, 0x2010, v4
	v_sub_u32_e32 v4, v58, v4
	v_cvt_f32_i32_e32 v56, v4
	v_pk_mul_f32 v[38:39], v[54:55], v[2:3]
	ds_bpermute_b32 v2, v207, v38
	ds_bpermute_b32 v3, v207, v39
	v_mul_f32_e32 v4, 0.15915494, v56
	v_fma_f32 v5, v56, 0.15915494, -v4
	v_fract_f32_e32 v4, v4
	v_fmac_f32_e32 v5, 0x31dc9c88, v56
	v_add_f32_e32 v4, v4, v5
	v_mul_f32_e32 v5, 0x3e4693af, v56
	v_mul_f32_e32 v7, 0.15915494, v5
	v_fma_f32 v8, v5, 0.15915494, -v7
	v_fract_f32_e32 v7, v7
	v_fmac_f32_e32 v8, 0x31dc9c88, v5
	v_add_f32_e32 v5, v7, v8
	v_mul_f32_e32 v8, 0x3d1a08c8, v56
	v_mul_f32_e32 v9, 0.15915494, v8
	v_fma_f32 v52, v8, 0.15915494, -v9
	v_fract_f32_e32 v9, v9
	v_fmac_f32_e32 v52, 0x31dc9c88, v8
	v_add_f32_e32 v8, v9, v52
	v_cos_f32_e32 v52, v8
	v_sin_f32_e32 v54, v8
	v_mul_f32_e32 v8, 0x3beef74e, v56
	v_mul_f32_e32 v9, 0.15915494, v8
	v_fma_f32 v53, v8, 0.15915494, -v9
	v_fract_f32_e32 v9, v9
	v_fmac_f32_e32 v53, 0x31dc9c88, v8
	ds_bpermute_b32 v50, v207, v40
	ds_bpermute_b32 v51, v207, v41
	v_add_f32_e32 v8, v9, v53
	v_cos_f32_e32 v6, v4
	v_sin_f32_e32 v4, v4
	v_cos_f32_e32 v7, v5
	v_sin_f32_e32 v5, v5
	v_cos_f32_e32 v53, v8
	v_sin_f32_e32 v55, v8
	v_mov_b32_e32 v42, v36
	v_mov_b32_e32 v43, v36
	v_cmp_lt_i32_e32 vcc, 0, v202
	s_and_saveexec_b64 s[2:3], vcc
	s_xor_b64 s[10:11], exec, s[2:3]
	s_cbranch_execz .LBB0_302
	v_cmp_eq_u32_e32 vcc, 1, v202
	s_and_saveexec_b64 s[14:15], vcc
	s_cbranch_execz .LBB0_301
	v_pk_mul_f32 v[8:9], v[52:53], v[40:41]
	v_pk_mul_f32 v[6:7], v[6:7], v[38:39]
	s_waitcnt lgkmcnt(0)
	v_pk_fma_f32 v[40:41], v[54:55], v[50:51], v[8:9]
	v_pk_fma_f32 v[38:39], v[4:5], v[2:3], v[6:7]

; #define LAS __attribute__((address_space(3)))
; __device__ __forceinline__ u32x4 pack8(const f32x4 a, const f32x4 b) { u32x4 w; w.x = cvtpk(a[0], a[1]); w.y = cvtpk(a[2], a[3]); w.z = cvtpk(b[0], b[1]); w.w = cvtpk(b[2], b[3]); return w; }
; __device__ __forceinline__ void rs_commit(LAS unsigned char* lds, const PrepRegs& r, int ui, int tid) {
;     const f32x4 s4 = r.a + r.b; float s = (s4[0] + s4[1]) + (s4[2] + s4[3]); s += __shfl_xor(s, 1);
;     if ((tid & 1) == 0) ((LAS float*)(lds + LDS_RSTAB))[(ui & 1) * 256 + (tid >> 1)] = rsqrtf(s * (1.0f / DM) + EPS);
; }
;     __device__ __forceinline__ void run(const f32x4 (&acc)[2][2][4][2], const Unit& u, int wr, int wc, int fr, int fq, const int nai, LAS unsigned char* lds, const int ui) const {
;     ...
;                 bf16_t* rowp = PJ + (size_t)r * NIN + pn * 256 + wc * 64 + 8 * fq;
; #pragma unroll
;                 for (int bj = 0; bj < 2; ++bj) *(u32x4*)(rowp + 32 * bj) = pack8(v[bj][0], v[bj][1]);
.LBB0_311:
	v_mov_b64_e32 v[2:3], s[16:17]
	v_mad_i64_i32 v[2:3], s[2:3], v58, s33, v[2:3]
	v_lshl_add_u64 v[2:3], s[8:9], 1, v[2:3]
	v_lshl_add_u64 v[2:3], v[2:3], 0, s[6:7]
	v_lshl_add_u64 v[8:9], v[2:3], 0, v[0:1]
	v_cvt_pk_bf16_f32 v2, v38, v39
	v_cvt_pk_bf16_f32 v3, v40, v41
	v_cvt_pk_bf16_f32 v4, v10, v11
	v_cvt_pk_bf16_f32 v5, v44, v45
	global_store_dwordx4 v[8:9], v[2:5], off
	s_waitcnt vmcnt(15)
	v_pk_add_f32 v[6:7], v[22:23], v[18:19]
	v_pk_add_f32 v[2:3], v[24:25], v[20:21]
	v_add_f32_e32 v0, v6, v7
	v_add_f32_e32 v2, v2, v3
	v_add_f32_e32 v0, v0, v2
	ds_bpermute_b32 v2, v193, v0
	v_cvt_pk_bf16_f32 v4, v34, v35
	v_cvt_pk_bf16_f32 v5, v12, v13
	v_cvt_pk_bf16_f32 v6, v16, v17
	v_cvt_pk_bf16_f32 v7, v14, v15
	global_store_dwordx4 v[8:9], v[4:7], off offset:64
	s_and_saveexec_b64 s[8:9], s[36:37]
	s_cbranch_execz .LBB0_313
	s_waitcnt lgkmcnt(0)
	v_add_f32_e32 v0, v0, v2
	v_fmamk_f32 v0, v0, 0x3a800000, v214
	s_mov_b32 s2, 0x800000
	v_cmp_gt_f32_e32 vcc, s2, v0
	v_mul_f32_e32 v2, 0x4b800000, v0
	s_lshl_b32 s2, s67, 10
	v_cndmask_b32_e32 v0, v0, v2, vcc
	v_rsq_f32_e32 v0, v0
	s_and_b32 s2, s2, 0x400
	v_mul_f32_e32 v2, 0x45800000, v0
	v_cndmask_b32_e32 v0, v0, v2, vcc
	v_add_u32_e32 v2, s2, v206
	ds_write_b32 v2, v0

; #define LAS __attribute__((address_space(3)))
; __device__ __forceinline__ u32x4 pack8(const f32x4 a, const f32x4 b) { u32x4 w; w.x = cvtpk(a[0], a[1]); w.y = cvtpk(a[2], a[3]); w.z = cvtpk(b[0], b[1]); w.w = cvtpk(b[2], b[3]); return w; }
;     __device__ __forceinline__ void run(const f32x4 (&acc)[2][2][4][2], const Unit& u, int wr, int wc, int fr, int fq, const int nai, LAS unsigned char* lds, const int ui) const {
;         const LAS float* RT = (const LAS float*)(lds + LDS_RSTAB) + (ui & 1) * 256;
; #pragma unroll
;         for (int ai = 0; ai < nai; ++ai)
; #pragma unroll
;             for (int m = 0; m < 4; ++m) {
;                 const int r = u.pm * 256 + ai * 128 + wr * 64 + m * 16 + fr;
;                 const float rs = RT[ai * 128 + wr * 64 + m * 16 + fr];
;                 f32x4 a[2];
; #pragma unroll
;                 for (int n = 0; n < 2; ++n) {
;                     const f32x4 g = acc[ai][0][m][n] * rs, uu = acc[ai][1][m][n] * rs;
; #pragma unroll
;                     for (int i = 0; i < 4; ++i) a[n][i] = g[i] * uu[i] * __builtin_amdgcn_rcpf(1.0f + __expf(-g[i]));
;                 }
;                 *(u32x4*)(ACT + (size_t)r * DFF + u.pn * 128 + wc * 32 + 8 * fq) = pack8(a[0], a[1]);
.LBB0_784:
	v_lshl_add_u32 v50, s59, 8, v154
	v_ashrrev_i32_e32 v51, 31, v50
	s_lshl_b32 s11, s34, 10
	v_lshlrev_b64 v[50:51], 6, v[50:51]
	s_and_b32 s11, s11, 0x400
	v_lshl_add_u64 v[54:55], v[146:147], 0, v[50:51]
	v_add_u32_e32 v162, s11, v158
	global_load_dwordx4 v[50:53], v[54:55], off
	s_nop 0
	global_load_dwordx4 v[54:57], v[54:55], off offset:16
	ds_read2_b32 v[152:153], v162 offset1:16
	s_lshl_b32 s46, s35, 7
	v_lshl_add_u32 v161, s58, 8, v156
	s_ashr_i32 s47, s46, 31
	s_movk_i32 s11, 0x1600
	s_waitcnt lgkmcnt(0)
	v_pk_mul_f32 v[134:135], v[134:135], v[152:153] op_sel_hi:[1,0]
	v_pk_mul_f32 v[130:131], v[130:131], v[152:153] op_sel_hi:[1,0]
	v_mul_f32_e32 v163, 0xbfb8aa3b, v134
	v_pk_mul_f32 v[130:131], v[134:135], v[130:131]
	v_mul_f32_e32 v134, 0xbfb8aa3b, v135
	v_exp_f32_e32 v134, v134
	v_pk_mul_f32 v[132:133], v[132:133], v[152:153] op_sel_hi:[1,0]
	v_pk_mul_f32 v[126:127], v[126:127], v[152:153] op_sel_hi:[1,0]
	v_pk_mul_f32 v[122:123], v[122:123], v[152:153] op_sel_hi:[1,0]
	v_add_f32_e32 v134, 1.0, v134
	v_rcp_f32_e32 v165, v134
	v_pk_mul_f32 v[134:135], v[136:137], v[152:153] op_sel_hi:[1,0]
	v_pk_mul_f32 v[122:123], v[126:127], v[122:123]
	v_mul_f32_e32 v136, 0xbfb8aa3b, v134
	v_pk_mul_f32 v[132:133], v[134:135], v[132:133]
	v_mul_f32_e32 v134, 0xbfb8aa3b, v135
	v_exp_f32_e32 v134, v134
	v_pk_mul_f32 v[124:125], v[124:125], v[152:153] op_sel_hi:[1,0]
	v_exp_f32_e32 v163, v163
	v_exp_f32_e32 v136, v136
	v_add_f32_e32 v134, 1.0, v134
	v_rcp_f32_e32 v137, v134
	v_mul_f32_e32 v134, 0xbfb8aa3b, v126
	v_mul_f32_e32 v126, 0xbfb8aa3b, v127
	v_exp_f32_e32 v126, v126
	v_exp_f32_e32 v134, v134
	v_add_f32_e32 v163, 1.0, v163
	v_add_f32_e32 v136, 1.0, v136
	v_add_f32_e32 v126, 1.0, v126
	v_rcp_f32_e32 v135, v126
	v_pk_mul_f32 v[126:127], v[128:129], v[152:153] op_sel_hi:[1,0]
	v_add_f32_e32 v134, 1.0, v134
	v_mul_f32_e32 v128, 0xbfb8aa3b, v126
	v_pk_mul_f32 v[124:125], v[126:127], v[124:125]
	v_mul_f32_e32 v126, 0xbfb8aa3b, v127
	v_exp_f32_e32 v128, v128
	v_exp_f32_e32 v126, v126
	v_rcp_f32_e32 v134, v134
	v_rcp_f32_e32 v164, v163
	v_add_f32_e32 v128, 1.0, v128
	v_add_f32_e32 v126, 1.0, v126
	v_rcp_f32_e32 v128, v128
	v_rcp_f32_e32 v129, v126
	v_rcp_f32_e32 v136, v136
	v_pk_mul_f32 v[122:123], v[122:123], v[134:135]
	s_lshl_b64 s[46:47], s[46:47], 1
	v_pk_mul_f32 v[128:129], v[124:125], v[128:129]
	v_cvt_pk_bf16_f32 v126, v122, v123
	v_mov_b64_e32 v[122:123], s[16:17]
	v_cvt_pk_bf16_f32 v127, v128, v129
	v_mad_i64_i32 v[128:129], s[30:31], v161, s11, v[122:123]
	v_lshl_add_u64 v[128:129], v[128:129], 0, s[46:47]
	v_pk_mul_f32 v[130:131], v[130:131], v[164:165]
	v_pk_mul_f32 v[132:133], v[132:133], v[136:137]
	v_lshl_add_u64 v[128:129], v[128:129], 0, s[6:7]
	v_cvt_pk_bf16_f32 v124, v130, v131
	v_cvt_pk_bf16_f32 v125, v132, v133
	v_lshl_add_u64 v[128:129], v[128:129], 0, v[0:1]
	global_store_dwordx4 v[128:129], v[124:127], off
	s_nop 1
	v_mov_b32_e32 v124, v153
	v_pk_mul_f32 v[118:119], v[118:119], v[124:125] op_sel_hi:[1,0]
	s_nop 0
	v_mul_f32_e32 v125, 0xbfb8aa3b, v118
	v_exp_f32_e32 v125, v125
	s_nop 0
	v_add_f32_e32 v125, 1.0, v125
	v_pk_mul_f32 v[114:115], v[114:115], v[124:125] op_sel_hi:[1,0]
	v_pk_mul_f32 v[116:117], v[116:117], v[124:125] op_sel_hi:[1,0]
	v_pk_mul_f32 v[114:115], v[118:119], v[114:115]
	v_mul_f32_e32 v118, 0xbfb8aa3b, v119
	v_exp_f32_e32 v118, v118
	v_pk_mul_f32 v[110:111], v[110:111], v[124:125] op_sel_hi:[1,0]
	v_pk_mul_f32 v[106:107], v[106:107], v[124:125] op_sel_hi:[1,0]
	v_pk_mul_f32 v[108:109], v[108:109], v[124:125] op_sel_hi:[1,0]
	v_add_f32_e32 v118, 1.0, v118
	v_rcp_f32_e32 v127, v118
	v_pk_mul_f32 v[118:119], v[120:121], v[124:125] op_sel_hi:[1,0]
	v_pk_mul_f32 v[106:107], v[110:111], v[106:107]
	v_mul_f32_e32 v120, 0xbfb8aa3b, v118
	v_pk_mul_f32 v[116:117], v[118:119], v[116:117]
	v_mul_f32_e32 v118, 0xbfb8aa3b, v119
	v_exp_f32_e32 v118, v118
	v_exp_f32_e32 v120, v120
	v_rcp_f32_e32 v126, v125
	v_add_f32_e32 v118, 1.0, v118
	v_rcp_f32_e32 v121, v118
	v_mul_f32_e32 v118, 0xbfb8aa3b, v110
	v_mul_f32_e32 v110, 0xbfb8aa3b, v111
	v_exp_f32_e32 v118, v118
	v_exp_f32_e32 v110, v110
	v_add_f32_e32 v120, 1.0, v120
	v_rcp_f32_e32 v120, v120
	v_add_f32_e32 v118, 1.0, v118
	v_add_f32_e32 v110, 1.0, v110
	v_rcp_f32_e32 v118, v118
	v_rcp_f32_e32 v119, v110
	v_pk_mul_f32 v[114:115], v[114:115], v[126:127]
	v_pk_mul_f32 v[116:117], v[116:117], v[120:121]
	v_pk_mul_f32 v[110:111], v[106:107], v[118:119]
	v_pk_mul_f32 v[106:107], v[112:113], v[124:125] op_sel_hi:[1,0]
	v_or_b32_e32 v118, 16, v161
	v_mul_f32_e32 v112, 0xbfb8aa3b, v106
	v_pk_mul_f32 v[108:109], v[106:107], v[108:109]
	v_mul_f32_e32 v106, 0xbfb8aa3b, v107
	v_exp_f32_e32 v112, v112
	v_exp_f32_e32 v106, v106
	v_cvt_pk_bf16_f32 v107, v116, v117
	v_add_f32_e32 v112, 1.0, v112
	v_add_f32_e32 v106, 1.0, v106
	v_rcp_f32_e32 v112, v112
	v_rcp_f32_e32 v113, v106
	v_cvt_pk_bf16_f32 v106, v114, v115
	v_pk_mul_f32 v[112:113], v[108:109], v[112:113]
	v_cvt_pk_bf16_f32 v108, v110, v111
	v_mad_i64_i32 v[110:111], s[30:31], v118, s11, v[122:123]
	v_lshl_add_u64 v[110:111], v[110:111], 0, s[46:47]
	v_lshl_add_u64 v[110:111], v[110:111], 0, s[6:7]
	v_cvt_pk_bf16_f32 v109, v112, v113
	v_lshl_add_u64 v[110:111], v[110:111], 0, v[0:1]
	global_store_dwordx4 v[110:111], v[106:109], off
	ds_read2_b32 v[106:107], v162 offset0:32 offset1:48
	s_waitcnt lgkmcnt(0)
; __device__ __forceinline__ u32x4 pack8(const f32x4 a, const f32x4 b) { u32x4 w; w.x = cvtpk(a[0], a[1]); w.y = cvtpk(a[2], a[3]); w.z = cvtpk(b[0], b[1]); w.w = cvtpk(b[2], b[3]); return w; }
;     __device__ __forceinline__ void run(const f32x4 (&acc)[2][2][4][2], const Unit& u, int wr, int wc, int fr, int fq, const int nai, LAS unsigned char* lds, const int ui) const {
;     ...
;         for (int ai = 0; ai < nai; ++ai)
; #pragma unroll
;             for (int m = 0; m < 4; ++m) {
;                 const int r = u.pm * 256 + ai * 128 + wr * 64 + m * 16 + fr;
;                 const float rs = RT[ai * 128 + wr * 64 + m * 16 + fr];
;                 f32x4 a[2];
; #pragma unroll
;                 for (int n = 0; n < 2; ++n) {
;                     const f32x4 g = acc[ai][0][m][n] * rs, uu = acc[ai][1][m][n] * rs;
; #pragma unroll
;                     for (int i = 0; i < 4; ++i) a[n][i] = g[i] * uu[i] * __builtin_amdgcn_rcpf(1.0f + __expf(-g[i]));
;                 }
;                 *(u32x4*)(ACT + (size_t)r * DFF + u.pn * 128 + wc * 32 + 8 * fq) = pack8(a[0], a[1]);
	v_pk_mul_f32 v[102:103], v[102:103], v[106:107] op_sel_hi:[1,0]
	v_pk_mul_f32 v[98:99], v[98:99], v[106:107] op_sel_hi:[1,0]
	v_mul_f32_e32 v108, 0xbfb8aa3b, v102
	v_pk_mul_f32 v[98:99], v[102:103], v[98:99]
	v_mul_f32_e32 v102, 0xbfb8aa3b, v103
	v_exp_f32_e32 v102, v102
	v_pk_mul_f32 v[100:101], v[100:101], v[106:107] op_sel_hi:[1,0]
	v_pk_mul_f32 v[94:95], v[94:95], v[106:107] op_sel_hi:[1,0]
	v_pk_mul_f32 v[90:91], v[90:91], v[106:107] op_sel_hi:[1,0]
	v_add_f32_e32 v102, 1.0, v102
	v_rcp_f32_e32 v109, v102
	v_pk_mul_f32 v[102:103], v[104:105], v[106:107] op_sel_hi:[1,0]
	v_pk_mul_f32 v[90:91], v[94:95], v[90:91]
	v_mul_f32_e32 v104, 0xbfb8aa3b, v102
	v_pk_mul_f32 v[100:101], v[102:103], v[100:101]
	v_mul_f32_e32 v102, 0xbfb8aa3b, v103
	v_exp_f32_e32 v102, v102
	v_pk_mul_f32 v[92:93], v[92:93], v[106:107] op_sel_hi:[1,0]
	v_exp_f32_e32 v108, v108
	v_exp_f32_e32 v104, v104
	v_add_f32_e32 v102, 1.0, v102
	v_rcp_f32_e32 v105, v102
	v_mul_f32_e32 v102, 0xbfb8aa3b, v94
	v_mul_f32_e32 v94, 0xbfb8aa3b, v95
	v_exp_f32_e32 v102, v102
	v_exp_f32_e32 v94, v94
	v_add_f32_e32 v108, 1.0, v108
	v_add_f32_e32 v104, 1.0, v104
	v_add_f32_e32 v102, 1.0, v102
	v_add_f32_e32 v94, 1.0, v94
	v_rcp_f32_e32 v102, v102
	v_rcp_f32_e32 v103, v94
	v_rcp_f32_e32 v108, v108
	v_rcp_f32_e32 v104, v104
	v_pk_mul_f32 v[94:95], v[90:91], v[102:103]
	v_pk_mul_f32 v[90:91], v[96:97], v[106:107] op_sel_hi:[1,0]
	v_or_b32_e32 v102, 32, v161
	v_mul_f32_e32 v96, 0xbfb8aa3b, v90
	v_pk_mul_f32 v[92:93], v[90:91], v[92:93]
	v_mul_f32_e32 v90, 0xbfb8aa3b, v91
	v_exp_f32_e32 v96, v96
	v_exp_f32_e32 v90, v90
	v_pk_mul_f32 v[98:99], v[98:99], v[108:109]
	v_pk_mul_f32 v[100:101], v[100:101], v[104:105]
	v_add_f32_e32 v96, 1.0, v96
	v_add_f32_e32 v90, 1.0, v90
	v_rcp_f32_e32 v96, v96
	v_rcp_f32_e32 v97, v90
	v_cvt_pk_bf16_f32 v90, v98, v99
	v_cvt_pk_bf16_f32 v91, v100, v101
	v_pk_mul_f32 v[96:97], v[92:93], v[96:97]
	v_cvt_pk_bf16_f32 v92, v94, v95
	v_mad_i64_i32 v[94:95], s[30:31], v102, s11, v[122:123]
	v_lshl_add_u64 v[94:95], v[94:95], 0, s[46:47]
	v_lshl_add_u64 v[94:95], v[94:95], 0, s[6:7]
	v_cvt_pk_bf16_f32 v93, v96, v97
	v_lshl_add_u64 v[94:95], v[94:95], 0, v[0:1]
	global_store_dwordx4 v[94:95], v[90:93], off
	s_nop 1
	v_mov_b32_e32 v90, v107
	v_pk_mul_f32 v[86:87], v[86:87], v[90:91] op_sel_hi:[1,0]
	s_nop 0
	v_mul_f32_e32 v91, 0xbfb8aa3b, v86
	v_exp_f32_e32 v91, v91
	s_nop 0
	v_add_f32_e32 v91, 1.0, v91
	v_pk_mul_f32 v[82:83], v[82:83], v[90:91] op_sel_hi:[1,0]
	v_pk_mul_f32 v[84:85], v[84:85], v[90:91] op_sel_hi:[1,0]
	v_pk_mul_f32 v[82:83], v[86:87], v[82:83]
	v_mul_f32_e32 v86, 0xbfb8aa3b, v87
	v_exp_f32_e32 v86, v86
	v_pk_mul_f32 v[78:79], v[78:79], v[90:91] op_sel_hi:[1,0]
	v_pk_mul_f32 v[74:75], v[74:75], v[90:91] op_sel_hi:[1,0]
	v_pk_mul_f32 v[76:77], v[76:77], v[90:91] op_sel_hi:[1,0]
	v_add_f32_e32 v86, 1.0, v86
	v_rcp_f32_e32 v93, v86
	v_pk_mul_f32 v[86:87], v[88:89], v[90:91] op_sel_hi:[1,0]
	v_pk_mul_f32 v[74:75], v[78:79], v[74:75]
	v_mul_f32_e32 v88, 0xbfb8aa3b, v86
	v_pk_mul_f32 v[84:85], v[86:87], v[84:85]
	v_mul_f32_e32 v86, 0xbfb8aa3b, v87
	v_exp_f32_e32 v86, v86
	v_exp_f32_e32 v88, v88
	v_rcp_f32_e32 v92, v91
	v_add_f32_e32 v86, 1.0, v86
	v_rcp_f32_e32 v89, v86
	v_mul_f32_e32 v86, 0xbfb8aa3b, v78
	v_mul_f32_e32 v78, 0xbfb8aa3b, v79
	v_exp_f32_e32 v86, v86
	v_exp_f32_e32 v78, v78
	v_add_f32_e32 v88, 1.0, v88
	v_rcp_f32_e32 v88, v88
	v_add_f32_e32 v86, 1.0, v86
	v_add_f32_e32 v78, 1.0, v78
	v_rcp_f32_e32 v86, v86
	v_rcp_f32_e32 v87, v78
	v_pk_mul_f32 v[82:83], v[82:83], v[92:93]
	v_pk_mul_f32 v[84:85], v[84:85], v[88:89]
	v_pk_mul_f32 v[78:79], v[74:75], v[86:87]
	v_pk_mul_f32 v[74:75], v[80:81], v[90:91] op_sel_hi:[1,0]
	v_or_b32_e32 v86, 48, v161
	v_mul_f32_e32 v80, 0xbfb8aa3b, v74
	v_pk_mul_f32 v[76:77], v[74:75], v[76:77]
	v_mul_f32_e32 v74, 0xbfb8aa3b, v75
	v_exp_f32_e32 v80, v80
	v_exp_f32_e32 v74, v74
	v_cvt_pk_bf16_f32 v75, v84, v85
	v_add_f32_e32 v80, 1.0, v80
	v_add_f32_e32 v74, 1.0, v74
	v_rcp_f32_e32 v80, v80
	v_rcp_f32_e32 v81, v74
	v_cvt_pk_bf16_f32 v74, v82, v83
	v_pk_mul_f32 v[80:81], v[76:77], v[80:81]
	v_cvt_pk_bf16_f32 v76, v78, v79
	v_mad_i64_i32 v[78:79], s[30:31], v86, s11, v[122:123]
	v_lshl_add_u64 v[78:79], v[78:79], 0, s[46:47]
	v_lshl_add_u64 v[78:79], v[78:79], 0, s[6:7]
	v_cvt_pk_bf16_f32 v77, v80, v81
	v_lshl_add_u64 v[78:79], v[78:79], 0, v[0:1]
	global_store_dwordx4 v[78:79], v[74:77], off
	ds_read2_b32 v[74:75], v162 offset0:128 offset1:144
	v_add_u32_e32 v78, 0x80, v161
	s_waitcnt lgkmcnt(0)
; __device__ __forceinline__ u32x4 pack8(const f32x4 a, const f32x4 b) { u32x4 w; w.x = cvtpk(a[0], a[1]); w.y = cvtpk(a[2], a[3]); w.z = cvtpk(b[0], b[1]); w.w = cvtpk(b[2], b[3]); return w; }
;     __device__ __forceinline__ void run(const f32x4 (&acc)[2][2][4][2], const Unit& u, int wr, int wc, int fr, int fq, const int nai, LAS unsigned char* lds, const int ui) const {
;     ...
;         for (int ai = 0; ai < nai; ++ai)
; #pragma unroll
;             for (int m = 0; m < 4; ++m) {
;                 const int r = u.pm * 256 + ai * 128 + wr * 64 + m * 16 + fr;
;                 const float rs = RT[ai * 128 + wr * 64 + m * 16 + fr];
;                 f32x4 a[2];
; #pragma unroll
;                 for (int n = 0; n < 2; ++n) {
;                     const f32x4 g = acc[ai][0][m][n] * rs, uu = acc[ai][1][m][n] * rs;
; #pragma unroll
;                     for (int i = 0; i < 4; ++i) a[n][i] = g[i] * uu[i] * __builtin_amdgcn_rcpf(1.0f + __expf(-g[i]));
;                 }
;                 *(u32x4*)(ACT + (size_t)r * DFF + u.pn * 128 + wc * 32 + 8 * fq) = pack8(a[0], a[1]);
	v_pk_mul_f32 v[70:71], v[70:71], v[74:75] op_sel_hi:[1,0]
	v_pk_mul_f32 v[66:67], v[66:67], v[74:75] op_sel_hi:[1,0]
	v_mul_f32_e32 v76, 0xbfb8aa3b, v70
	v_pk_mul_f32 v[66:67], v[70:71], v[66:67]
	v_mul_f32_e32 v70, 0xbfb8aa3b, v71
	v_exp_f32_e32 v70, v70
	v_pk_mul_f32 v[68:69], v[68:69], v[74:75] op_sel_hi:[1,0]
	v_pk_mul_f32 v[62:63], v[62:63], v[74:75] op_sel_hi:[1,0]
	v_pk_mul_f32 v[58:59], v[58:59], v[74:75] op_sel_hi:[1,0]
	v_add_f32_e32 v70, 1.0, v70
	v_rcp_f32_e32 v77, v70
	v_pk_mul_f32 v[70:71], v[72:73], v[74:75] op_sel_hi:[1,0]
	v_pk_mul_f32 v[58:59], v[62:63], v[58:59]
	v_mul_f32_e32 v72, 0xbfb8aa3b, v70
	v_pk_mul_f32 v[68:69], v[70:71], v[68:69]
	v_mul_f32_e32 v70, 0xbfb8aa3b, v71
	v_exp_f32_e32 v70, v70
	v_pk_mul_f32 v[60:61], v[60:61], v[74:75] op_sel_hi:[1,0]
	v_exp_f32_e32 v76, v76
	v_exp_f32_e32 v72, v72
	v_add_f32_e32 v70, 1.0, v70
	v_rcp_f32_e32 v73, v70
	v_mul_f32_e32 v70, 0xbfb8aa3b, v62
	v_mul_f32_e32 v62, 0xbfb8aa3b, v63
	v_exp_f32_e32 v70, v70
	v_exp_f32_e32 v62, v62
	v_add_f32_e32 v76, 1.0, v76
	v_add_f32_e32 v72, 1.0, v72
	v_add_f32_e32 v70, 1.0, v70
	v_add_f32_e32 v62, 1.0, v62
	v_rcp_f32_e32 v70, v70
	v_rcp_f32_e32 v71, v62
	v_rcp_f32_e32 v76, v76
	v_rcp_f32_e32 v72, v72
	v_pk_mul_f32 v[62:63], v[58:59], v[70:71]
	v_pk_mul_f32 v[58:59], v[64:65], v[74:75] op_sel_hi:[1,0]
	v_pk_mul_f32 v[66:67], v[66:67], v[76:77]
	v_mul_f32_e32 v64, 0xbfb8aa3b, v58
	v_pk_mul_f32 v[60:61], v[58:59], v[60:61]
	v_mul_f32_e32 v58, 0xbfb8aa3b, v59
	v_exp_f32_e32 v64, v64
	v_exp_f32_e32 v58, v58
	v_pk_mul_f32 v[68:69], v[68:69], v[72:73]
	v_add_f32_e32 v64, 1.0, v64
	v_add_f32_e32 v58, 1.0, v58
	v_rcp_f32_e32 v64, v64
	v_rcp_f32_e32 v65, v58
	v_cvt_pk_bf16_f32 v58, v66, v67
	v_cvt_pk_bf16_f32 v59, v68, v69
	v_pk_mul_f32 v[64:65], v[60:61], v[64:65]
	v_cvt_pk_bf16_f32 v60, v62, v63
	v_mad_i64_i32 v[62:63], s[30:31], v78, s11, v[122:123]
	v_lshl_add_u64 v[62:63], v[62:63], 0, s[46:47]
	v_lshl_add_u64 v[62:63], v[62:63], 0, s[6:7]
	v_cvt_pk_bf16_f32 v61, v64, v65
	v_lshl_add_u64 v[62:63], v[62:63], 0, v[0:1]
	global_store_dwordx4 v[62:63], v[58:61], off
	s_nop 1
	v_mov_b32_e32 v58, v75
	v_pk_mul_f32 v[46:47], v[46:47], v[58:59] op_sel_hi:[1,0]
	s_nop 0
	v_mul_f32_e32 v59, 0xbfb8aa3b, v46
	v_exp_f32_e32 v59, v59
	s_nop 0
	v_add_f32_e32 v59, 1.0, v59
	v_pk_mul_f32 v[42:43], v[42:43], v[58:59] op_sel_hi:[1,0]
	v_pk_mul_f32 v[44:45], v[44:45], v[58:59] op_sel_hi:[1,0]
	v_pk_mul_f32 v[42:43], v[46:47], v[42:43]
	v_mul_f32_e32 v46, 0xbfb8aa3b, v47
	v_exp_f32_e32 v46, v46
	v_pk_mul_f32 v[38:39], v[38:39], v[58:59] op_sel_hi:[1,0]
	v_pk_mul_f32 v[34:35], v[34:35], v[58:59] op_sel_hi:[1,0]
	v_pk_mul_f32 v[36:37], v[36:37], v[58:59] op_sel_hi:[1,0]
	v_add_f32_e32 v46, 1.0, v46
	v_rcp_f32_e32 v61, v46
	v_pk_mul_f32 v[46:47], v[48:49], v[58:59] op_sel_hi:[1,0]
	v_pk_mul_f32 v[34:35], v[38:39], v[34:35]
	v_mul_f32_e32 v48, 0xbfb8aa3b, v46
	v_pk_mul_f32 v[44:45], v[46:47], v[44:45]
	v_mul_f32_e32 v46, 0xbfb8aa3b, v47
	v_exp_f32_e32 v46, v46
	v_exp_f32_e32 v48, v48
	v_rcp_f32_e32 v60, v59
	v_add_f32_e32 v46, 1.0, v46
	v_rcp_f32_e32 v49, v46
	v_mul_f32_e32 v46, 0xbfb8aa3b, v38
	v_mul_f32_e32 v38, 0xbfb8aa3b, v39
	v_exp_f32_e32 v46, v46
	v_exp_f32_e32 v38, v38
	v_add_f32_e32 v48, 1.0, v48
	v_rcp_f32_e32 v48, v48
	v_add_f32_e32 v46, 1.0, v46
	v_add_f32_e32 v38, 1.0, v38
	v_rcp_f32_e32 v46, v46
	v_rcp_f32_e32 v47, v38
	v_pk_mul_f32 v[42:43], v[42:43], v[60:61]
	v_pk_mul_f32 v[44:45], v[44:45], v[48:49]
	v_pk_mul_f32 v[38:39], v[34:35], v[46:47]
	v_pk_mul_f32 v[34:35], v[40:41], v[58:59] op_sel_hi:[1,0]
	v_add_u32_e32 v46, 0x90, v161
	v_mul_f32_e32 v40, 0xbfb8aa3b, v34
	v_pk_mul_f32 v[36:37], v[34:35], v[36:37]
	v_mul_f32_e32 v34, 0xbfb8aa3b, v35
	v_exp_f32_e32 v40, v40
	v_exp_f32_e32 v34, v34
	v_cvt_pk_bf16_f32 v35, v44, v45
	v_add_f32_e32 v40, 1.0, v40
	v_add_f32_e32 v34, 1.0, v34
	v_rcp_f32_e32 v40, v40
	v_rcp_f32_e32 v41, v34
	v_cvt_pk_bf16_f32 v34, v42, v43
	v_pk_mul_f32 v[40:41], v[36:37], v[40:41]
	v_cvt_pk_bf16_f32 v36, v38, v39
	v_mad_i64_i32 v[38:39], s[30:31], v46, s11, v[122:123]
	v_lshl_add_u64 v[38:39], v[38:39], 0, s[46:47]
	v_lshl_add_u64 v[38:39], v[38:39], 0, s[6:7]
	v_cvt_pk_bf16_f32 v37, v40, v41
	v_lshl_add_u64 v[38:39], v[38:39], 0, v[0:1]
	global_store_dwordx4 v[38:39], v[34:37], off
	ds_read2_b32 v[34:35], v162 offset0:160 offset1:176
	s_waitcnt lgkmcnt(0)
; #define LAS __attribute__((address_space(3)))
; __device__ __forceinline__ u32x4 pack8(const f32x4 a, const f32x4 b) { u32x4 w; w.x = cvtpk(a[0], a[1]); w.y = cvtpk(a[2], a[3]); w.z = cvtpk(b[0], b[1]); w.w = cvtpk(b[2], b[3]); return w; }
; __device__ __forceinline__ void rs_commit(LAS unsigned char* lds, const PrepRegs& r, int ui, int tid) {
;     const f32x4 s4 = r.a + r.b; float s = (s4[0] + s4[1]) + (s4[2] + s4[3]); s += __shfl_xor(s, 1);
;     if ((tid & 1) == 0) ((LAS float*)(lds + LDS_RSTAB))[(ui & 1) * 256 + (tid >> 1)] = rsqrtf(s * (1.0f / DM) + EPS);
; }
;     __device__ __forceinline__ void run(const f32x4 (&acc)[2][2][4][2], const Unit& u, int wr, int wc, int fr, int fq, const int nai, LAS unsigned char* lds, const int ui) const {
;     ...
;         for (int ai = 0; ai < nai; ++ai)
; #pragma unroll
;             for (int m = 0; m < 4; ++m) {
;                 const int r = u.pm * 256 + ai * 128 + wr * 64 + m * 16 + fr;
;                 const float rs = RT[ai * 128 + wr * 64 + m * 16 + fr];
;                 f32x4 a[2];
; #pragma unroll
;                 for (int n = 0; n < 2; ++n) {
;                     const f32x4 g = acc[ai][0][m][n] * rs, uu = acc[ai][1][m][n] * rs;
; #pragma unroll
;                     for (int i = 0; i < 4; ++i) a[n][i] = g[i] * uu[i] * __builtin_amdgcn_rcpf(1.0f + __expf(-g[i]));
;                 }
;                 *(u32x4*)(ACT + (size_t)r * DFF + u.pn * 128 + wc * 32 + 8 * fq) = pack8(a[0], a[1]);
	v_pk_mul_f32 v[30:31], v[30:31], v[34:35] op_sel_hi:[1,0]
	v_pk_mul_f32 v[26:27], v[26:27], v[34:35] op_sel_hi:[1,0]
	v_mul_f32_e32 v36, 0xbfb8aa3b, v30
	v_pk_mul_f32 v[26:27], v[30:31], v[26:27]
	v_mul_f32_e32 v30, 0xbfb8aa3b, v31
	v_exp_f32_e32 v30, v30
	v_pk_mul_f32 v[28:29], v[28:29], v[34:35] op_sel_hi:[1,0]
	v_pk_mul_f32 v[22:23], v[22:23], v[34:35] op_sel_hi:[1,0]
	v_pk_mul_f32 v[18:19], v[18:19], v[34:35] op_sel_hi:[1,0]
	v_add_f32_e32 v30, 1.0, v30
	v_rcp_f32_e32 v37, v30
	v_pk_mul_f32 v[30:31], v[32:33], v[34:35] op_sel_hi:[1,0]
	v_pk_mul_f32 v[18:19], v[22:23], v[18:19]
	v_mul_f32_e32 v32, 0xbfb8aa3b, v30
	v_pk_mul_f32 v[28:29], v[30:31], v[28:29]
	v_mul_f32_e32 v30, 0xbfb8aa3b, v31
	v_exp_f32_e32 v30, v30
	v_pk_mul_f32 v[20:21], v[20:21], v[34:35] op_sel_hi:[1,0]
	v_exp_f32_e32 v36, v36
	v_exp_f32_e32 v32, v32
	v_add_f32_e32 v30, 1.0, v30
	v_rcp_f32_e32 v33, v30
	v_mul_f32_e32 v30, 0xbfb8aa3b, v22
	v_mul_f32_e32 v22, 0xbfb8aa3b, v23
	v_exp_f32_e32 v30, v30
	v_exp_f32_e32 v22, v22
	v_add_f32_e32 v36, 1.0, v36
	v_add_f32_e32 v32, 1.0, v32
	v_add_f32_e32 v30, 1.0, v30
	v_add_f32_e32 v22, 1.0, v22
	v_rcp_f32_e32 v30, v30
	v_rcp_f32_e32 v31, v22
	v_rcp_f32_e32 v36, v36
	v_rcp_f32_e32 v32, v32
	v_pk_mul_f32 v[22:23], v[18:19], v[30:31]
	v_pk_mul_f32 v[18:19], v[24:25], v[34:35] op_sel_hi:[1,0]
	v_add_u32_e32 v30, 0xa0, v161
	v_mul_f32_e32 v24, 0xbfb8aa3b, v18
	v_pk_mul_f32 v[20:21], v[18:19], v[20:21]
	v_mul_f32_e32 v18, 0xbfb8aa3b, v19
	v_exp_f32_e32 v24, v24
	v_exp_f32_e32 v18, v18
	v_pk_mul_f32 v[26:27], v[26:27], v[36:37]
	v_pk_mul_f32 v[28:29], v[28:29], v[32:33]
	v_add_f32_e32 v24, 1.0, v24
	v_add_f32_e32 v18, 1.0, v18
	v_rcp_f32_e32 v24, v24
	v_rcp_f32_e32 v25, v18
	v_cvt_pk_bf16_f32 v18, v26, v27
	v_cvt_pk_bf16_f32 v19, v28, v29
	v_pk_mul_f32 v[24:25], v[20:21], v[24:25]
	v_cvt_pk_bf16_f32 v20, v22, v23
	v_mad_i64_i32 v[22:23], s[30:31], v30, s11, v[122:123]
	v_lshl_add_u64 v[22:23], v[22:23], 0, s[46:47]
	v_lshl_add_u64 v[22:23], v[22:23], 0, s[6:7]
	v_cvt_pk_bf16_f32 v21, v24, v25
	v_lshl_add_u64 v[22:23], v[22:23], 0, v[0:1]
	global_store_dwordx4 v[22:23], v[18:21], off
	s_nop 1
	v_mov_b32_e32 v18, v35
	v_pk_mul_f32 v[14:15], v[14:15], v[18:19] op_sel_hi:[1,0]
	s_nop 0
	v_mul_f32_e32 v19, 0xbfb8aa3b, v14
	v_exp_f32_e32 v19, v19
	s_nop 0
	v_add_f32_e32 v19, 1.0, v19
	v_pk_mul_f32 v[10:11], v[10:11], v[18:19] op_sel_hi:[1,0]
	v_pk_mul_f32 v[12:13], v[12:13], v[18:19] op_sel_hi:[1,0]
	v_pk_mul_f32 v[10:11], v[14:15], v[10:11]
	v_mul_f32_e32 v14, 0xbfb8aa3b, v15
	v_exp_f32_e32 v14, v14
	v_pk_mul_f32 v[6:7], v[6:7], v[18:19] op_sel_hi:[1,0]
	v_pk_mul_f32 v[2:3], v[2:3], v[18:19] op_sel_hi:[1,0]
	v_pk_mul_f32 v[4:5], v[4:5], v[18:19] op_sel_hi:[1,0]
	v_add_f32_e32 v14, 1.0, v14
	v_rcp_f32_e32 v21, v14
	v_pk_mul_f32 v[14:15], v[16:17], v[18:19] op_sel_hi:[1,0]
	v_pk_mul_f32 v[2:3], v[6:7], v[2:3]
	v_mul_f32_e32 v16, 0xbfb8aa3b, v14
	v_pk_mul_f32 v[12:13], v[14:15], v[12:13]
	v_mul_f32_e32 v14, 0xbfb8aa3b, v15
	v_exp_f32_e32 v14, v14
	v_exp_f32_e32 v16, v16
	v_rcp_f32_e32 v20, v19
	v_add_f32_e32 v14, 1.0, v14
	v_rcp_f32_e32 v17, v14
	v_mul_f32_e32 v14, 0xbfb8aa3b, v6
	v_mul_f32_e32 v6, 0xbfb8aa3b, v7
	v_exp_f32_e32 v14, v14
	v_exp_f32_e32 v6, v6
	v_add_f32_e32 v16, 1.0, v16
	v_rcp_f32_e32 v16, v16
	v_add_f32_e32 v14, 1.0, v14
	v_add_f32_e32 v6, 1.0, v6
	v_rcp_f32_e32 v14, v14
	v_rcp_f32_e32 v15, v6
	v_pk_mul_f32 v[10:11], v[10:11], v[20:21]
	v_pk_mul_f32 v[12:13], v[12:13], v[16:17]
	v_pk_mul_f32 v[6:7], v[2:3], v[14:15]
	v_pk_mul_f32 v[2:3], v[8:9], v[18:19] op_sel_hi:[1,0]
	v_add_u32_e32 v14, 0xb0, v161
	v_mul_f32_e32 v8, 0xbfb8aa3b, v2
	v_pk_mul_f32 v[4:5], v[2:3], v[4:5]
	v_mul_f32_e32 v2, 0xbfb8aa3b, v3
	v_exp_f32_e32 v8, v8
	v_exp_f32_e32 v2, v2
	v_cvt_pk_bf16_f32 v3, v12, v13
	v_add_f32_e32 v8, 1.0, v8
	v_add_f32_e32 v2, 1.0, v2
	v_rcp_f32_e32 v8, v8
	v_rcp_f32_e32 v9, v2
	v_cvt_pk_bf16_f32 v2, v10, v11
	v_pk_mul_f32 v[8:9], v[4:5], v[8:9]
	v_cvt_pk_bf16_f32 v4, v6, v7
	v_mad_i64_i32 v[6:7], s[30:31], v14, s11, v[122:123]
	v_lshl_add_u64 v[6:7], v[6:7], 0, s[46:47]
	v_lshl_add_u64 v[6:7], v[6:7], 0, s[6:7]
	v_cvt_pk_bf16_f32 v5, v8, v9
	v_lshl_add_u64 v[6:7], v[6:7], 0, v[0:1]
	global_store_dwordx4 v[6:7], v[2:5], off
	s_waitcnt vmcnt(8)
	s_nop 0
	v_pk_add_f32 v[2:3], v[52:53], v[56:57]
	v_pk_add_f32 v[4:5], v[50:51], v[54:55]
	v_add_f32_e32 v2, v2, v3
	v_add_f32_e32 v4, v4, v5
	v_add_f32_e32 v2, v4, v2
	ds_bpermute_b32 v3, v155, v2
	s_and_saveexec_b64 s[46:47], s[40:41]
	s_cbranch_execz .LBB0_786
	s_waitcnt lgkmcnt(0)
	v_add_f32_e32 v2, v2, v3
	v_fmamk_f32 v2, v2, 0x3a800000, v214
	s_mov_b32 s11, 0x800000
	v_cmp_gt_f32_e32 vcc, s11, v2
	v_mul_f32_e32 v3, 0x4b800000, v2
	s_lshl_b32 s11, s27, 10
	v_cndmask_b32_e32 v2, v2, v3, vcc
	v_rsq_f32_e32 v2, v2
	s_and_b32 s11, s11, 0x400
	v_mul_f32_e32 v3, 0x45800000, v2
	v_cndmask_b32_e32 v2, v2, v3, vcc
	v_add_u32_e32 v3, s11, v159
	ds_write_b32 v3, v2
